# in-proj tile loop: next tile's first K-tile fetched behind one barrier right after the current tile's last LDS reads (lands under the epilogue)
# baseline (speedup 1.0000x reference)
;     DEVINL bf16_t* Win() const { return (bf16_t*)(ws + OFF_WIN); }
;     DEVINL bf16_t* H() const { return (bf16_t*)(ws + OFF_RW); }
; DEVINL void phase_inproj(const Ctx& c, int layer, unsigned char* lds, bool trivial = false) {
;     ...
;     for (int q = slot; q < (halves ? nfull : total); q += G) {
;         int tm, tn; tile_of(q, MT, NT, tm, tn);
;         f32x16 acc[2][2]; zero_acc(acc);
;         gemm_kloop<2>(c.H(), DM, c.Win(), DM, DM, tm * 256, tn * 128, lds, acc);
.LBB0_361:
	s_and_b64 s[0:1], s[0:1], exec
	v_readlane_b32 s0, v246, 19
	s_cselect_b32 s35, s0, 0x1474
	s_cmp_ge_i32 s34, s35
	s_cbranch_scc1 .LBB0_540
	v_readlane_b32 s0, v245, 32
	v_readlane_b32 s1, v245, 33
	s_lshl_b32 s0, s0, 6
	s_ashr_i32 s1, s0, 31
	v_readlane_b32 s8, v245, 11
	s_lshl_b64 s[4:5], s[0:1], 2
	v_readlane_b32 s14, v245, 17
	v_readlane_b32 s15, v245, 18
	s_add_u32 s0, s14, s4
	v_readlane_b32 s12, v245, 15
	s_addc_u32 s1, s15, s5
	v_readlane_b32 s13, v245, 16
	s_add_u32 s4, s12, s4
	v_lshlrev_b32_e32 v73, 6, v112
	v_lshlrev_b32_e32 v92, 6, v113
	s_addc_u32 s5, s13, s5
	v_readlane_b32 s9, v245, 12
	v_readlane_b32 s10, v245, 13
	v_readlane_b32 s11, v245, 14
	v_readlane_b32 s16, v245, 19
	v_readlane_b32 s17, v245, 20
	v_readlane_b32 s18, v245, 21
	v_readlane_b32 s19, v245, 22
	v_readlane_b32 s20, v245, 23
	v_readlane_b32 s21, v245, 24
	v_readlane_b32 s22, v245, 25
	v_readlane_b32 s23, v245, 26
	v_mov_b32_e32 v201, 0
	s_branch .LBB0_364

; #define TID (opq_v((int)threadIdx.x))
; template <int NI>
; DEVINL void gemm_kloop(const bf16_t* __restrict__ A, int lda, const bf16_t* __restrict__ Bt, int ldb, int K, int m0, int n0,
;                        unsigned char* lds, f32x16 (&acc)[NI][2]) {
;     const int tid = TID, lane = tid & 63, w = tid >> 6, wm = w & 3, wn = w >> 2, r = lane & 31, h = lane >> 5;
;     const int lrow = tid >> 3, cg = (tid & 7) ^ ((tid >> 4) & 7);
;     const bf16_t* ga = A + (size_t)(m0 + lrow) * lda + cg * 8;
;     const bf16_t* gb = Bt + (size_t)(n0 + lrow) * ldb + cg * 8;
;     unsigned char* da = lds + tid * 16;
;     unsigned char* db = lds + A_ST + tid * 16;
;     ...
;     const int nt = K >> 6;
;     asm volatile("s_waitcnt lgkmcnt(0)" ::: "memory");
;     __builtin_amdgcn_s_barrier();
;     GEMM_ISSUE(0, 0);
;     if (nt > 1) GEMM_ISSUE(1, 1);
.LBB0_364:
	s_add_i32 s100, s34, s70
	s_cmp_lt_i32 s100, s35
	s_cselect_b32 s101, 1, 0
	v_mov_b32_e32 v200, s101
	s_mul_hi_i32 s6, s100, 0x78787879
	s_lshr_b32 s7, s6, 31
	s_ashr_i32 s6, s6, 8
	s_add_i32 s6, s6, s7
	s_lshl_b32 s7, s6, 3
	s_sub_i32 s8, 0x4d, s7
	s_min_i32 s8, s8, 8
	s_abs_i32 s9, s8
	v_cvt_f32_u32_e32 v0, s9
	s_sub_i32 s10, 0, s9
	s_mulk_i32 s6, 0xfde0
	s_add_i32 s6, s100, s6
	v_rcp_iflag_f32_e32 v0, v0
	s_nop 0
	v_mul_f32_e32 v0, 0x4f7ffffe, v0
	v_cvt_u32_f32_e32 v0, v0
	s_nop 0
	v_readfirstlane_b32 s11, v0
	s_mul_i32 s10, s10, s11
	s_mul_hi_u32 s10, s11, s10
	s_add_i32 s11, s11, s10
	s_abs_i32 s10, s6
	s_mul_hi_u32 s11, s10, s11
	s_mul_i32 s12, s11, s9
	s_sub_i32 s10, s10, s12
	s_xor_b32 s12, s6, s8
	s_ashr_i32 s12, s12, 31
	s_add_i32 s13, s11, 1
	s_sub_i32 s14, s10, s9
	s_cmp_ge_u32 s10, s9
	s_cselect_b32 s11, s13, s11
	s_cselect_b32 s10, s14, s10
	s_add_i32 s13, s11, 1
	s_cmp_ge_u32 s10, s9
	s_cselect_b32 s9, s13, s11
	s_xor_b32 s9, s9, s12
	s_sub_i32 s9, s9, s12
	s_lshl_b32 s36, s9, 8
	s_mul_i32 s8, s9, s8
	s_sub_i32 s6, s6, s8
	s_add_i32 s6, s6, s7
	s_lshl_b32 s6, s6, 7
	v_mov_b32_e32 v202, s36
	v_mov_b32_e32 v204, s6
	s_mul_hi_i32 s6, s34, 0x78787879
	s_lshr_b32 s7, s6, 31
	s_ashr_i32 s6, s6, 8
	s_add_i32 s6, s6, s7
	s_lshl_b32 s7, s6, 3
	s_sub_i32 s8, 0x4d, s7
	s_min_i32 s8, s8, 8
	s_abs_i32 s9, s8
	v_cvt_f32_u32_e32 v0, s9
	s_sub_i32 s10, 0, s9
	s_mulk_i32 s6, 0xfde0
	s_add_i32 s6, s34, s6
	v_rcp_iflag_f32_e32 v0, v0
	v_mov_b32_e32 v70, v160
	s_waitcnt lgkmcnt(0)
	v_mul_f32_e32 v0, 0x4f7ffffe, v0
	v_cvt_u32_f32_e32 v0, v0
	v_ashrrev_i32_e32 v2, 3, v70
	v_lshl_add_u32 v91, v70, 4, 0
	v_add_u32_e32 v93, 0x2000, v91
	v_readfirstlane_b32 s11, v0
	s_mul_i32 s10, s10, s11
	s_mul_hi_u32 s10, s11, s10
	s_add_i32 s11, s11, s10
	s_abs_i32 s10, s6
	s_mul_hi_u32 s11, s10, s11
	s_mul_i32 s12, s11, s9
	s_sub_i32 s10, s10, s12
	s_xor_b32 s12, s6, s8
	s_ashr_i32 s12, s12, 31
	s_add_i32 s13, s11, 1
	s_sub_i32 s14, s10, s9
	s_cmp_ge_u32 s10, s9
	s_cselect_b32 s11, s13, s11
	s_cselect_b32 s10, s14, s10
	s_add_i32 s13, s11, 1
	s_cmp_ge_u32 s10, s9
	s_cselect_b32 s9, s13, s11
	s_xor_b32 s9, s9, s12
	s_sub_i32 s9, s9, s12
	s_lshl_b32 s36, s9, 8
	v_lshrrev_b32_e32 v0, 4, v70
	s_mul_i32 s8, s9, s8
	v_xor_b32_e32 v3, v0, v70
	v_add_u32_e32 v0, s36, v2
	s_sub_i32 s6, s6, s8
	v_ashrrev_i32_e32 v1, 31, v0
	v_readlane_b32 s8, v245, 28
	s_add_i32 s6, s6, s7
	v_lshlrev_b64 v[0:1], 11, v[0:1]
	v_readlane_b32 s9, v245, 29
	v_lshlrev_b32_e32 v3, 4, v3
	s_lshl_b32 s6, s6, 7
	v_lshl_add_u64 v[0:1], s[8:9], 0, v[0:1]
	v_and_b32_e32 v64, 0x70, v3
	v_lshl_add_u64 v[66:67], v[0:1], 0, v[64:65]
	v_add_u32_e32 v0, s6, v2
	v_ashrrev_i32_e32 v1, 31, v0
	v_readlane_b32 s8, v246, 27
	v_readfirstlane_b32 s11, v91
	v_lshlrev_b64 v[0:1], 11, v[0:1]
	v_readlane_b32 s9, v246, 28
	s_mov_b32 m0, s11
	v_readfirstlane_b32 s12, v93
	v_add_u32_e32 v94, 0x4000, v91
	v_lshl_add_u64 v[0:1], s[8:9], 0, v[0:1]
	v_readfirstlane_b32 s100, v201
	s_cmp_eq_u32 s100, 1
	s_cselect_b64 s[100:101], 0, -1
	s_barrier
	s_mov_b64 exec, s[100:101]
	global_load_lds_dwordx4 v[66:67], off
	s_mov_b64 exec, -1
	v_lshl_add_u64 v[2:3], v[66:67], 0, s[68:69]
	s_mov_b32 m0, s12
	s_mov_b64 s[8:9], 0x40000
	v_readfirstlane_b32 s13, v94
	v_add_u32_e32 v96, 0x6000, v91
	v_add_u32_e32 v90, 0x8000, v91
	s_mov_b64 exec, s[100:101]
	global_load_lds_dwordx4 v[2:3], off
	s_mov_b64 exec, -1
	v_lshl_add_u64 v[2:3], v[66:67], 0, s[8:9]
	s_mov_b32 m0, s13
	s_mov_b64 s[8:9], 0x60000
	v_readfirstlane_b32 s14, v96
	s_mov_b64 exec, s[100:101]
	global_load_lds_dwordx4 v[2:3], off
	s_mov_b64 exec, -1
	v_lshl_add_u64 v[2:3], v[66:67], 0, s[8:9]
	s_mov_b32 m0, s14
	v_readfirstlane_b32 s15, v90
	v_add_u32_e32 v95, 0xa000, v91
	s_mov_b64 exec, s[100:101]
	global_load_lds_dwordx4 v[2:3], off
	s_mov_b64 exec, -1
	v_lshl_add_u64 v[68:69], v[0:1], 0, v[64:65]
	v_subrev_u32_e32 v202, s36, v202
	v_ashrrev_i32_e32 v203, 31, v202
	v_lshlrev_b64 v[202:203], 11, v[202:203]
	v_lshl_add_u64 v[202:203], v[66:67], 0, v[202:203]
	v_subrev_u32_e32 v204, s6, v204
	v_ashrrev_i32_e32 v205, 31, v204
	v_lshlrev_b64 v[204:205], 11, v[204:205]
	v_lshl_add_u64 v[204:205], v[68:69], 0, v[204:205]
	s_mov_b32 m0, s15
	v_readfirstlane_b32 s16, v95
	v_add_u32_e32 v103, 0xc000, v91
	s_mov_b64 exec, s[100:101]
	global_load_lds_dwordx4 v[68:69], off
	s_mov_b64 exec, -1
	v_lshl_add_u64 v[0:1], v[68:69], 0, s[68:69]
	s_mov_b32 m0, s16
	v_readfirstlane_b32 s25, v103
	v_add_u32_e32 v104, 0xe000, v91
	s_mov_b64 exec, s[100:101]
	global_load_lds_dwordx4 v[0:1], off
	s_mov_b64 exec, -1
	v_lshl_add_u64 v[0:1], v[66:67], 0, s[92:93]
	s_mov_b32 m0, s25
	v_readfirstlane_b32 s26, v104
	v_add_u32_e32 v2, 0x10000, v91
	global_load_lds_dwordx4 v[0:1], off
	v_lshl_add_u64 v[0:1], v[66:67], 0, s[60:61]
	s_mov_b32 m0, s26
	s_mov_b64 s[8:9], 0x40080
	v_readfirstlane_b32 s7, v2
	global_load_lds_dwordx4 v[0:1], off
	v_lshl_add_u64 v[0:1], v[66:67], 0, s[8:9]
	s_mov_b32 m0, s7
	s_mov_b64 s[8:9], 0x60080
	v_add_u32_e32 v2, 0x12000, v91
	global_load_lds_dwordx4 v[0:1], off
	v_lshl_add_u64 v[0:1], v[66:67], 0, s[8:9]
	v_readfirstlane_b32 s8, v2
	v_add_u32_e32 v2, 0x14000, v91
	s_mov_b32 m0, s8
	v_readfirstlane_b32 s9, v2
	v_add_u32_e32 v2, 0x16000, v91
	global_load_lds_dwordx4 v[0:1], off
	v_lshl_add_u64 v[0:1], v[68:69], 0, s[92:93]
	s_mov_b32 m0, s9
	v_readfirstlane_b32 s10, v2
	global_load_lds_dwordx4 v[0:1], off
	v_lshl_add_u64 v[0:1], v[68:69], 0, s[60:61]
	s_mov_b32 m0, s10
	v_bfe_u32 v75, v70, 1, 3
	global_load_lds_dwordx4 v[0:1], off
	v_lshrrev_b32_e32 v0, 5, v70
	v_bitop3_b32 v0, v0, v75, 1 bitop3:0x6c
	v_lshlrev_b32_e32 v4, 7, v70
	v_lshlrev_b32_e32 v105, 4, v0
	v_and_b32_e32 v0, 0xf80, v4
	v_lshlrev_b32_e32 v1, 5, v70
	s_movk_i32 s17, 0xe000
	v_add_u32_e32 v97, 0x18000, v91
	v_and_or_b32 v114, v1, s17, v0
	v_readfirstlane_b32 s17, v97
	v_add_u32_e32 v98, 0x1a000, v91
	v_lshl_add_u64 v[0:1], v[66:67], 0, s[84:85]
	s_mov_b32 m0, s17
	s_mov_b64 s[28:29], 0x20100
	v_readfirstlane_b32 s18, v98
	v_add_u32_e32 v99, 0x1c000, v91
	s_waitcnt vmcnt(6)
	s_barrier
; #define MFMA32(a, b, c) __builtin_amdgcn_mfma_f32_32x32x16_bf16((a), (b), (c), 0, 0, 0)
; template <int NI>
; DEVINL void gemm_kloop(const bf16_t* __restrict__ A, int lda, const bf16_t* __restrict__ Bt, int ldb, int K, int m0, int n0,
;                        unsigned char* lds, f32x16 (&acc)[NI][2]) {
;     ...
;     if (nt > 1) GEMM_ISSUE(1, 1);
;     const int sw = (r >> 1) & 7;
;     int o4[4];
; #pragma unroll
;     for (int ks = 0; ks < 4; ++ks) o4[ks] = ((ks * 2 + h) ^ sw) * 16;
;     int cur = 0;
;     auto compute = [&](int st_) {
;         const unsigned char* pa = lds + st_ * STAGE + (wm * 64 + r) * 128;
;         const unsigned char* pb = lds + st_ * STAGE + A_ST + (wn * 32 * NI + r) * 128;
;         bf16x8 af[2][2], bfr[2][NI];
; #pragma unroll
;         for (int i = 0; i < 2; ++i) af[0][i] = *(const bf16x8*)(pa + i * 32 * 128 + o4[0]);
; #pragma unroll
;         for (int i = 0; i < NI; ++i) bfr[0][i] = *(const bf16x8*)(pb + i * 32 * 128 + o4[0]);
; #pragma unroll
;         for (int ks = 0; ks < 4; ++ks) {
;             if (ks < 3) {
; #pragma unroll
;                 for (int i = 0; i < 2; ++i) af[(ks + 1) & 1][i] = *(const bf16x8*)(pa + i * 32 * 128 + o4[ks + 1]);
; #pragma unroll
;                 for (int i = 0; i < NI; ++i) bfr[(ks + 1) & 1][i] = *(const bf16x8*)(pb + i * 32 * 128 + o4[ks + 1]);
;             }
; #pragma unroll
;             for (int ni = 0; ni < NI; ++ni)
; #pragma unroll
;                 for (int mi = 0; mi < 2; ++mi) acc[ni][mi] = MFMA32(bfr[ks & 1][ni], af[ks & 1][mi], acc[ni][mi]);
;         }
;     };
;     int t = 0;
;     for (; t + 2 < nt; ++t) {
;         if (NI == 2) asm volatile("s_waitcnt vmcnt(6)" ::: "memory"); else asm volatile("s_waitcnt vmcnt(5)" ::: "memory");
;         __builtin_amdgcn_s_barrier();
;         { const int s2 = (cur >= 1) ? cur - 1 : 2; GEMM_ISSUE(s2, t + 2); }
;         compute(cur);
	global_load_lds_dwordx4 v[0:1], off
	v_lshl_add_u64 v[0:1], v[66:67], 0, s[28:29]
	s_mov_b32 m0, s18
	s_mov_b64 s[20:21], 0x40100
	v_readfirstlane_b32 s19, v99
	global_load_lds_dwordx4 v[0:1], off
	v_lshl_add_u64 v[0:1], v[66:67], 0, s[20:21]
	s_mov_b32 m0, s19
	s_mov_b64 s[20:21], 0x60100
	v_add_u32_e32 v100, 0x1e000, v91
	global_load_lds_dwordx4 v[0:1], off
	v_lshl_add_u64 v[0:1], v[66:67], 0, s[20:21]
	v_readfirstlane_b32 s20, v100
	v_add_u32_e32 v101, 0x20000, v91
	s_mov_b32 m0, s20
	v_readfirstlane_b32 s21, v101
	v_add_u32_e32 v102, 0x22000, v91
	global_load_lds_dwordx4 v[0:1], off
	v_lshl_add_u64 v[0:1], v[68:69], 0, s[84:85]
	s_mov_b32 m0, s21
	v_readfirstlane_b32 s24, v102
	global_load_lds_dwordx4 v[0:1], off
	v_lshl_add_u64 v[0:1], v[68:69], 0, s[28:29]
	s_mov_b32 m0, s24
	v_add_u32_e32 v110, 0, v114
	global_load_lds_dwordx4 v[0:1], off
	v_add_u32_e32 v64, v110, v105
	ds_read_b128 v[0:3], v64 offset:32768
	v_and_b32_e32 v115, 0x6f80, v4
	v_add_u32_e32 v111, 0, v115
	v_add_u32_e32 v71, v111, v105
	ds_read_b128 v[4:7], v71
	ds_read_b128 v[8:11], v71 offset:4096
	ds_read_b128 v[12:15], v64 offset:36864
	v_bfe_u32 v112, v70, 5, 1
	s_waitcnt lgkmcnt(0)
	v_mfma_f32_32x32x16_bf16 v[48:63], v[0:3], v[4:7], 0
	v_bitop3_b32 v72, v112, v75, 4 bitop3:0x36
	v_lshlrev_b32_e32 v122, 4, v72
	v_add_u32_e32 v72, v110, v122
	s_mov_b32 m0, s11
	s_mov_b64 s[28:29], 0x40180
	s_add_i32 s27, 0, 0x14000
	v_add_u32_e32 v116, s27, v114
	v_mfma_f32_32x32x16_bf16 v[16:31], v[0:3], v[8:11], 0
	v_bitop3_b32 v0, v112, v75, 2 bitop3:0x36
	v_lshlrev_b32_e32 v118, 4, v0
	v_add_u32_e32 v70, v110, v118
	ds_read_b128 v[76:79], v70 offset:32768
	v_add_u32_e32 v74, v111, v118
	ds_read_b128 v[80:83], v74
	ds_read_b128 v[84:87], v74 offset:4096
	ds_read_b128 v[106:109], v70 offset:36864
	v_bitop3_b32 v75, v112, v75, 6 bitop3:0x36
	v_mfma_f32_32x32x16_bf16 v[32:47], v[12:15], v[4:7], 0
	v_lshlrev_b32_e32 v123, 4, v75
	v_add_u32_e32 v75, v110, v123
	v_add_u32_e32 v125, s42, v114
	s_add_i32 s27, 0, 0x18000
	v_add_u32_e32 v124, s27, v115
	s_mov_b64 s[30:31], 0x40400
	s_mov_b64 s[52:53], 0x40680
	v_mfma_f32_32x32x16_bf16 v[0:15], v[12:15], v[8:11], 0
	s_waitcnt lgkmcnt(0)
	v_mfma_f32_32x32x16_bf16 v[48:63], v[76:79], v[80:83], v[48:63]
	v_mfma_f32_32x32x16_bf16 v[16:31], v[76:79], v[84:87], v[16:31]
	v_add_u32_e32 v76, v111, v122
	v_add_u32_e32 v77, v111, v123
	v_mfma_f32_32x32x16_bf16 v[32:47], v[106:109], v[80:83], v[32:47]
	ds_read_b128 v[78:81], v72 offset:32768
	v_mfma_f32_32x32x16_bf16 v[0:15], v[106:109], v[84:87], v[0:15]
	ds_read_b128 v[82:85], v76
	ds_read_b128 v[86:89], v76 offset:4096
	ds_read_b128 v[106:109], v72 offset:36864
	s_waitcnt lgkmcnt(0)
	v_mfma_f32_32x32x16_bf16 v[48:63], v[78:81], v[82:85], v[48:63]
	v_mfma_f32_32x32x16_bf16 v[16:31], v[78:81], v[86:89], v[16:31]
	ds_read_b128 v[78:81], v75 offset:32768
	v_mfma_f32_32x32x16_bf16 v[32:47], v[106:109], v[82:85], v[32:47]
	v_mfma_f32_32x32x16_bf16 v[0:15], v[106:109], v[86:89], v[0:15]
	ds_read_b128 v[82:85], v77
	ds_read_b128 v[86:89], v77 offset:4096
	ds_read_b128 v[106:109], v75 offset:36864
	s_waitcnt vmcnt(6)
	s_barrier
	s_waitcnt lgkmcnt(0)
	v_mfma_f32_32x32x16_bf16 v[48:63], v[78:81], v[82:85], v[48:63]
	v_mfma_f32_32x32x16_bf16 v[16:31], v[78:81], v[86:89], v[16:31]
	v_lshl_add_u64 v[78:79], v[66:67], 0, s[88:89]
	global_load_lds_dwordx4 v[78:79], off
	v_lshl_add_u64 v[78:79], v[66:67], 0, s[56:57]
	s_mov_b32 m0, s12
	s_nop 0
	global_load_lds_dwordx4 v[78:79], off
	v_lshl_add_u64 v[78:79], v[66:67], 0, s[28:29]
	s_mov_b32 m0, s13
	s_mov_b64 s[28:29], 0x60180
	global_load_lds_dwordx4 v[78:79], off
	v_lshl_add_u64 v[78:79], v[66:67], 0, s[28:29]
	s_mov_b32 m0, s14
	v_mfma_f32_32x32x16_bf16 v[32:47], v[106:109], v[82:85], v[32:47]
	global_load_lds_dwordx4 v[78:79], off
	v_lshl_add_u64 v[78:79], v[68:69], 0, s[88:89]
	s_mov_b32 m0, s15
	s_mov_b64 s[28:29], 0x40200
	global_load_lds_dwordx4 v[78:79], off
	v_lshl_add_u64 v[78:79], v[68:69], 0, s[56:57]
	s_mov_b32 m0, s16
	v_mfma_f32_32x32x16_bf16 v[0:15], v[106:109], v[86:89], v[0:15]
	global_load_lds_dwordx4 v[78:79], off
	v_add_u32_e32 v78, v116, v105
	ds_read_b128 v[80:83], v78
	ds_read_b128 v[84:87], v71 offset:49152
	ds_read_b128 v[106:109], v71 offset:53248
	ds_read_b128 v[110:113], v78 offset:4096
	v_add_u32_e32 v79, v116, v118
	s_mov_b32 m0, s25
	s_waitcnt lgkmcnt(0)
	v_mfma_f32_32x32x16_bf16 v[48:63], v[80:83], v[84:87], v[48:63]
	v_mfma_f32_32x32x16_bf16 v[16:31], v[80:83], v[106:109], v[16:31]
	v_mfma_f32_32x32x16_bf16 v[32:47], v[110:113], v[84:87], v[32:47]
	v_mfma_f32_32x32x16_bf16 v[0:15], v[110:113], v[106:109], v[0:15]
	ds_read_b128 v[80:83], v79
	ds_read_b128 v[84:87], v74 offset:49152
	ds_read_b128 v[106:109], v74 offset:53248
	ds_read_b128 v[110:113], v79 offset:4096
	s_waitcnt lgkmcnt(0)
	v_mfma_f32_32x32x16_bf16 v[48:63], v[80:83], v[84:87], v[48:63]
	v_mfma_f32_32x32x16_bf16 v[16:31], v[80:83], v[106:109], v[16:31]
	v_add_u32_e32 v80, v116, v122
	v_add_u32_e32 v81, v116, v123
	v_mfma_f32_32x32x16_bf16 v[32:47], v[110:113], v[84:87], v[32:47]
	v_mfma_f32_32x32x16_bf16 v[0:15], v[110:113], v[106:109], v[0:15]
	ds_read_b128 v[82:85], v80
	ds_read_b128 v[86:89], v76 offset:49152
	ds_read_b128 v[106:109], v76 offset:53248
	ds_read_b128 v[110:113], v80 offset:4096
	s_waitcnt lgkmcnt(0)
	v_mfma_f32_32x32x16_bf16 v[48:63], v[82:85], v[86:89], v[48:63]
	v_mfma_f32_32x32x16_bf16 v[16:31], v[82:85], v[106:109], v[16:31]
	v_mfma_f32_32x32x16_bf16 v[32:47], v[110:113], v[86:89], v[32:47]
	v_mfma_f32_32x32x16_bf16 v[0:15], v[110:113], v[106:109], v[0:15]
	ds_read_b128 v[82:85], v81
	ds_read_b128 v[86:89], v77 offset:49152
	ds_read_b128 v[106:109], v77 offset:53248
	ds_read_b128 v[110:113], v81 offset:4096
	s_waitcnt vmcnt(6)
	s_barrier
; #define MFMA32(a, b, c) __builtin_amdgcn_mfma_f32_32x32x16_bf16((a), (b), (c), 0, 0, 0)
; template <int NI>
; DEVINL void gemm_kloop(const bf16_t* __restrict__ A, int lda, const bf16_t* __restrict__ Bt, int ldb, int K, int m0, int n0,
;                        unsigned char* lds, f32x16 (&acc)[NI][2]) {
;     ...
;     auto compute = [&](int st_) {
;         const unsigned char* pa = lds + st_ * STAGE + (wm * 64 + r) * 128;
;         const unsigned char* pb = lds + st_ * STAGE + A_ST + (wn * 32 * NI + r) * 128;
;         bf16x8 af[2][2], bfr[2][NI];
; #pragma unroll
;         for (int i = 0; i < 2; ++i) af[0][i] = *(const bf16x8*)(pa + i * 32 * 128 + o4[0]);
; #pragma unroll
;         for (int i = 0; i < NI; ++i) bfr[0][i] = *(const bf16x8*)(pb + i * 32 * 128 + o4[0]);
; #pragma unroll
;         for (int ks = 0; ks < 4; ++ks) {
;             if (ks < 3) {
; #pragma unroll
;                 for (int i = 0; i < 2; ++i) af[(ks + 1) & 1][i] = *(const bf16x8*)(pa + i * 32 * 128 + o4[ks + 1]);
; #pragma unroll
;                 for (int i = 0; i < NI; ++i) bfr[(ks + 1) & 1][i] = *(const bf16x8*)(pb + i * 32 * 128 + o4[ks + 1]);
;             }
; #pragma unroll
;             for (int ni = 0; ni < NI; ++ni)
; #pragma unroll
;                 for (int mi = 0; mi < 2; ++mi) acc[ni][mi] = MFMA32(bfr[ks & 1][ni], af[ks & 1][mi], acc[ni][mi]);
;         }
;     };
;     int t = 0;
;     for (; t + 2 < nt; ++t) {
;         if (NI == 2) asm volatile("s_waitcnt vmcnt(6)" ::: "memory"); else asm volatile("s_waitcnt vmcnt(5)" ::: "memory");
;         __builtin_amdgcn_s_barrier();
;         { const int s2 = (cur >= 1) ? cur - 1 : 2; GEMM_ISSUE(s2, t + 2); }
;         compute(cur);
;         cur = (cur == 2) ? 0 : cur + 1;
;     }
	s_waitcnt lgkmcnt(0)
	v_mfma_f32_32x32x16_bf16 v[48:63], v[82:85], v[86:89], v[48:63]
	v_mfma_f32_32x32x16_bf16 v[16:31], v[82:85], v[106:109], v[16:31]
	v_lshl_add_u64 v[82:83], v[66:67], 0, s[58:59]
	global_load_lds_dwordx4 v[82:83], off
	v_lshl_add_u64 v[82:83], v[66:67], 0, s[96:97]
	s_mov_b32 m0, s26
	v_add_u32_e32 v84, v124, v105
	global_load_lds_dwordx4 v[82:83], off
	v_lshl_add_u64 v[82:83], v[66:67], 0, s[28:29]
	s_mov_b32 m0, s7
	s_mov_b64 s[28:29], 0x60200
	global_load_lds_dwordx4 v[82:83], off
	v_lshl_add_u64 v[82:83], v[66:67], 0, s[28:29]
	s_mov_b32 m0, s8
	v_mfma_f32_32x32x16_bf16 v[32:47], v[110:113], v[86:89], v[32:47]
	global_load_lds_dwordx4 v[82:83], off
	v_lshl_add_u64 v[82:83], v[68:69], 0, s[58:59]
	s_mov_b32 m0, s9
	v_add_u32_e32 v85, v125, v122
	global_load_lds_dwordx4 v[82:83], off
	v_lshl_add_u64 v[82:83], v[68:69], 0, s[96:97]
	s_mov_b32 m0, s10
	v_mfma_f32_32x32x16_bf16 v[0:15], v[110:113], v[106:109], v[0:15]
	global_load_lds_dwordx4 v[82:83], off
	v_add_u32_e32 v82, v125, v105
	ds_read_b128 v[86:89], v82
	ds_read_b128 v[106:109], v84
	ds_read_b128 v[110:113], v84 offset:4096
	ds_read_b128 v[114:117], v82 offset:4096
	v_add_u32_e32 v83, v125, v118
	s_mov_b32 m0, s17
	s_waitcnt lgkmcnt(0)
	v_mfma_f32_32x32x16_bf16 v[48:63], v[86:89], v[106:109], v[48:63]
	s_mov_b64 s[28:29], 0x40280
	v_mfma_f32_32x32x16_bf16 v[32:47], v[114:117], v[106:109], v[32:47]
	ds_read_b128 v[106:109], v83
	v_mfma_f32_32x32x16_bf16 v[16:31], v[86:89], v[110:113], v[16:31]
	v_add_u32_e32 v86, v124, v118
	v_add_u32_e32 v87, v124, v122
	v_add_u32_e32 v88, v125, v123
	v_add_u32_e32 v89, v124, v123
	v_mfma_f32_32x32x16_bf16 v[0:15], v[114:117], v[110:113], v[0:15]
	ds_read_b128 v[110:113], v86
	ds_read_b128 v[114:117], v86 offset:4096
	ds_read_b128 v[118:121], v83 offset:4096
	s_waitcnt lgkmcnt(0)
	v_mfma_f32_32x32x16_bf16 v[48:63], v[106:109], v[110:113], v[48:63]
	v_mfma_f32_32x32x16_bf16 v[16:31], v[106:109], v[114:117], v[16:31]
	ds_read_b128 v[106:109], v85
	v_mfma_f32_32x32x16_bf16 v[32:47], v[118:121], v[110:113], v[32:47]
	v_mfma_f32_32x32x16_bf16 v[0:15], v[118:121], v[114:117], v[0:15]
	ds_read_b128 v[110:113], v87
	ds_read_b128 v[114:117], v87 offset:4096
	ds_read_b128 v[118:121], v85 offset:4096
	s_waitcnt lgkmcnt(0)
	v_mfma_f32_32x32x16_bf16 v[48:63], v[106:109], v[110:113], v[48:63]
	v_mfma_f32_32x32x16_bf16 v[16:31], v[106:109], v[114:117], v[16:31]
	ds_read_b128 v[106:109], v88
	v_mfma_f32_32x32x16_bf16 v[32:47], v[118:121], v[110:113], v[32:47]
	v_mfma_f32_32x32x16_bf16 v[0:15], v[118:121], v[114:117], v[0:15]
	ds_read_b128 v[110:113], v89
	ds_read_b128 v[114:117], v89 offset:4096
	ds_read_b128 v[118:121], v88 offset:4096
	s_waitcnt vmcnt(6)
	s_barrier
	s_waitcnt lgkmcnt(0)
	v_mfma_f32_32x32x16_bf16 v[48:63], v[106:109], v[110:113], v[48:63]
	v_mfma_f32_32x32x16_bf16 v[16:31], v[106:109], v[114:117], v[16:31]
	v_lshl_add_u64 v[106:107], v[66:67], 0, s[64:65]
	global_load_lds_dwordx4 v[106:107], off
	v_lshl_add_u64 v[106:107], v[66:67], 0, s[62:63]
	s_mov_b32 m0, s18
	s_nop 0
	global_load_lds_dwordx4 v[106:107], off
	v_lshl_add_u64 v[106:107], v[66:67], 0, s[28:29]
	s_mov_b32 m0, s19
	s_mov_b64 s[28:29], 0x60280
	global_load_lds_dwordx4 v[106:107], off
	v_lshl_add_u64 v[106:107], v[66:67], 0, s[28:29]
	s_mov_b32 m0, s20
	v_mfma_f32_32x32x16_bf16 v[32:47], v[118:121], v[110:113], v[32:47]
	global_load_lds_dwordx4 v[106:107], off
	v_lshl_add_u64 v[106:107], v[68:69], 0, s[64:65]
	s_mov_b32 m0, s21
	s_mov_b64 s[28:29], 0x40300
	global_load_lds_dwordx4 v[106:107], off
	v_lshl_add_u64 v[106:107], v[68:69], 0, s[62:63]
	s_mov_b32 m0, s24
	v_mfma_f32_32x32x16_bf16 v[0:15], v[118:121], v[114:117], v[0:15]
	global_load_lds_dwordx4 v[106:107], off
	ds_read_b128 v[106:109], v64 offset:32768
	ds_read_b128 v[110:113], v71
	ds_read_b128 v[114:117], v71 offset:4096
	ds_read_b128 v[118:121], v64 offset:36864
	s_mov_b32 m0, s11
	s_waitcnt lgkmcnt(0)
	v_mfma_f32_32x32x16_bf16 v[48:63], v[106:109], v[110:113], v[48:63]
	v_mfma_f32_32x32x16_bf16 v[16:31], v[106:109], v[114:117], v[16:31]
	v_mfma_f32_32x32x16_bf16 v[32:47], v[118:121], v[110:113], v[32:47]
	v_mfma_f32_32x32x16_bf16 v[0:15], v[118:121], v[114:117], v[0:15]
	ds_read_b128 v[106:109], v70 offset:32768
	ds_read_b128 v[110:113], v74
	ds_read_b128 v[114:117], v74 offset:4096
	ds_read_b128 v[118:121], v70 offset:36864
	s_waitcnt lgkmcnt(0)
	v_mfma_f32_32x32x16_bf16 v[48:63], v[106:109], v[110:113], v[48:63]
	v_mfma_f32_32x32x16_bf16 v[16:31], v[106:109], v[114:117], v[16:31]
	v_mfma_f32_32x32x16_bf16 v[32:47], v[118:121], v[110:113], v[32:47]
	v_mfma_f32_32x32x16_bf16 v[0:15], v[118:121], v[114:117], v[0:15]
	ds_read_b128 v[106:109], v72 offset:32768
	ds_read_b128 v[110:113], v76
	ds_read_b128 v[114:117], v76 offset:4096
	ds_read_b128 v[118:121], v72 offset:36864
	s_waitcnt lgkmcnt(0)
	v_mfma_f32_32x32x16_bf16 v[48:63], v[106:109], v[110:113], v[48:63]
	v_mfma_f32_32x32x16_bf16 v[16:31], v[106:109], v[114:117], v[16:31]
	v_mfma_f32_32x32x16_bf16 v[32:47], v[118:121], v[110:113], v[32:47]
	v_mfma_f32_32x32x16_bf16 v[0:15], v[118:121], v[114:117], v[0:15]
	ds_read_b128 v[106:109], v75 offset:32768
	ds_read_b128 v[110:113], v77
	ds_read_b128 v[114:117], v77 offset:4096
	ds_read_b128 v[118:121], v75 offset:36864
	s_waitcnt vmcnt(6)
	s_barrier
; #define MFMA32(a, b, c) __builtin_amdgcn_mfma_f32_32x32x16_bf16((a), (b), (c), 0, 0, 0)
; template <int NI>
; DEVINL void gemm_kloop(const bf16_t* __restrict__ A, int lda, const bf16_t* __restrict__ Bt, int ldb, int K, int m0, int n0,
;                        unsigned char* lds, f32x16 (&acc)[NI][2]) {
;     ...
;     auto compute = [&](int st_) {
;         const unsigned char* pa = lds + st_ * STAGE + (wm * 64 + r) * 128;
;         const unsigned char* pb = lds + st_ * STAGE + A_ST + (wn * 32 * NI + r) * 128;
;         bf16x8 af[2][2], bfr[2][NI];
; #pragma unroll
;         for (int i = 0; i < 2; ++i) af[0][i] = *(const bf16x8*)(pa + i * 32 * 128 + o4[0]);
; #pragma unroll
;         for (int i = 0; i < NI; ++i) bfr[0][i] = *(const bf16x8*)(pb + i * 32 * 128 + o4[0]);
; #pragma unroll
;         for (int ks = 0; ks < 4; ++ks) {
;             if (ks < 3) {
; #pragma unroll
;                 for (int i = 0; i < 2; ++i) af[(ks + 1) & 1][i] = *(const bf16x8*)(pa + i * 32 * 128 + o4[ks + 1]);
; #pragma unroll
;                 for (int i = 0; i < NI; ++i) bfr[(ks + 1) & 1][i] = *(const bf16x8*)(pb + i * 32 * 128 + o4[ks + 1]);
;             }
; #pragma unroll
;             for (int ni = 0; ni < NI; ++ni)
; #pragma unroll
;                 for (int mi = 0; mi < 2; ++mi) acc[ni][mi] = MFMA32(bfr[ks & 1][ni], af[ks & 1][mi], acc[ni][mi]);
;         }
;     };
;     int t = 0;
;     for (; t + 2 < nt; ++t) {
;         if (NI == 2) asm volatile("s_waitcnt vmcnt(6)" ::: "memory"); else asm volatile("s_waitcnt vmcnt(5)" ::: "memory");
;         __builtin_amdgcn_s_barrier();
;         { const int s2 = (cur >= 1) ? cur - 1 : 2; GEMM_ISSUE(s2, t + 2); }
;         compute(cur);
;         cur = (cur == 2) ? 0 : cur + 1;
;     }
	s_waitcnt lgkmcnt(0)
	v_mfma_f32_32x32x16_bf16 v[48:63], v[106:109], v[110:113], v[48:63]
	v_mfma_f32_32x32x16_bf16 v[16:31], v[106:109], v[114:117], v[16:31]
	v_lshl_add_u64 v[106:107], v[66:67], 0, s[2:3]
	global_load_lds_dwordx4 v[106:107], off
	v_lshl_add_u64 v[106:107], v[66:67], 0, s[90:91]
	s_mov_b32 m0, s12
	s_nop 0
	global_load_lds_dwordx4 v[106:107], off
	v_lshl_add_u64 v[106:107], v[66:67], 0, s[28:29]
	s_mov_b32 m0, s13
	s_mov_b64 s[28:29], 0x60300
	global_load_lds_dwordx4 v[106:107], off
	v_lshl_add_u64 v[106:107], v[66:67], 0, s[28:29]
	s_mov_b32 m0, s14
	v_mfma_f32_32x32x16_bf16 v[32:47], v[118:121], v[110:113], v[32:47]
	global_load_lds_dwordx4 v[106:107], off
	v_lshl_add_u64 v[106:107], v[68:69], 0, s[2:3]
	s_mov_b32 m0, s15
	s_mov_b64 s[28:29], 0x20400
	global_load_lds_dwordx4 v[106:107], off
	v_lshl_add_u64 v[106:107], v[68:69], 0, s[90:91]
	s_mov_b32 m0, s16
	v_mfma_f32_32x32x16_bf16 v[0:15], v[118:121], v[114:117], v[0:15]
	global_load_lds_dwordx4 v[106:107], off
	ds_read_b128 v[106:109], v78
	ds_read_b128 v[110:113], v71 offset:49152
	ds_read_b128 v[114:117], v71 offset:53248
	ds_read_b128 v[118:121], v78 offset:4096
	s_mov_b32 m0, s25
	s_waitcnt lgkmcnt(0)
	v_mfma_f32_32x32x16_bf16 v[48:63], v[106:109], v[110:113], v[48:63]
	v_mfma_f32_32x32x16_bf16 v[16:31], v[106:109], v[114:117], v[16:31]
	v_mfma_f32_32x32x16_bf16 v[32:47], v[118:121], v[110:113], v[32:47]
	v_mfma_f32_32x32x16_bf16 v[0:15], v[118:121], v[114:117], v[0:15]
	ds_read_b128 v[106:109], v79
	ds_read_b128 v[110:113], v74 offset:49152
	ds_read_b128 v[114:117], v74 offset:53248
	ds_read_b128 v[118:121], v79 offset:4096
	s_waitcnt lgkmcnt(0)
	v_mfma_f32_32x32x16_bf16 v[48:63], v[106:109], v[110:113], v[48:63]
	v_mfma_f32_32x32x16_bf16 v[16:31], v[106:109], v[114:117], v[16:31]
	v_mfma_f32_32x32x16_bf16 v[32:47], v[118:121], v[110:113], v[32:47]
	v_mfma_f32_32x32x16_bf16 v[0:15], v[118:121], v[114:117], v[0:15]
	ds_read_b128 v[106:109], v80
	ds_read_b128 v[110:113], v76 offset:49152
	ds_read_b128 v[114:117], v76 offset:53248
	ds_read_b128 v[118:121], v80 offset:4096
	s_waitcnt lgkmcnt(0)
	v_mfma_f32_32x32x16_bf16 v[48:63], v[106:109], v[110:113], v[48:63]
	v_mfma_f32_32x32x16_bf16 v[16:31], v[106:109], v[114:117], v[16:31]
	v_mfma_f32_32x32x16_bf16 v[32:47], v[118:121], v[110:113], v[32:47]
	v_mfma_f32_32x32x16_bf16 v[0:15], v[118:121], v[114:117], v[0:15]
	ds_read_b128 v[106:109], v81
	ds_read_b128 v[110:113], v77 offset:49152
	ds_read_b128 v[114:117], v77 offset:53248
	ds_read_b128 v[118:121], v81 offset:4096
	s_waitcnt vmcnt(6)
	s_barrier
	s_waitcnt lgkmcnt(0)
	v_mfma_f32_32x32x16_bf16 v[48:63], v[106:109], v[110:113], v[48:63]
	v_mfma_f32_32x32x16_bf16 v[16:31], v[106:109], v[114:117], v[16:31]
	v_lshl_add_u64 v[106:107], v[66:67], 0, s[40:41]
	global_load_lds_dwordx4 v[106:107], off
	v_lshl_add_u64 v[106:107], v[66:67], 0, s[72:73]
	s_mov_b32 m0, s26
	s_mov_b64 s[26:27], 0x40380
	global_load_lds_dwordx4 v[106:107], off
	v_lshl_add_u64 v[106:107], v[66:67], 0, s[26:27]
	s_mov_b32 m0, s7
	s_mov_b64 s[26:27], 0x60380
	global_load_lds_dwordx4 v[106:107], off
	v_lshl_add_u64 v[106:107], v[66:67], 0, s[26:27]
	s_mov_b32 m0, s8
	v_mfma_f32_32x32x16_bf16 v[32:47], v[118:121], v[110:113], v[32:47]
	global_load_lds_dwordx4 v[106:107], off
	v_lshl_add_u64 v[106:107], v[68:69], 0, s[40:41]
	s_mov_b32 m0, s9
	s_mov_b64 s[26:27], 0x400
	global_load_lds_dwordx4 v[106:107], off
	v_lshl_add_u64 v[106:107], v[68:69], 0, s[72:73]
	s_mov_b32 m0, s10
	v_mfma_f32_32x32x16_bf16 v[0:15], v[118:121], v[114:117], v[0:15]
	global_load_lds_dwordx4 v[106:107], off
	ds_read_b128 v[106:109], v82
	ds_read_b128 v[110:113], v84
	ds_read_b128 v[114:117], v84 offset:4096
	ds_read_b128 v[118:121], v82 offset:4096
	s_mov_b32 m0, s17
	s_waitcnt lgkmcnt(0)
	v_mfma_f32_32x32x16_bf16 v[48:63], v[106:109], v[110:113], v[48:63]
	v_mfma_f32_32x32x16_bf16 v[16:31], v[106:109], v[114:117], v[16:31]
	v_mfma_f32_32x32x16_bf16 v[32:47], v[118:121], v[110:113], v[32:47]
	v_mfma_f32_32x32x16_bf16 v[0:15], v[118:121], v[114:117], v[0:15]
	ds_read_b128 v[106:109], v83
	ds_read_b128 v[110:113], v86
	ds_read_b128 v[114:117], v86 offset:4096
	ds_read_b128 v[118:121], v83 offset:4096
	s_waitcnt lgkmcnt(0)
	v_mfma_f32_32x32x16_bf16 v[48:63], v[106:109], v[110:113], v[48:63]
	v_mfma_f32_32x32x16_bf16 v[16:31], v[106:109], v[114:117], v[16:31]
	v_mfma_f32_32x32x16_bf16 v[32:47], v[118:121], v[110:113], v[32:47]
	v_mfma_f32_32x32x16_bf16 v[0:15], v[118:121], v[114:117], v[0:15]
	ds_read_b128 v[106:109], v85
	ds_read_b128 v[110:113], v87
	ds_read_b128 v[114:117], v87 offset:4096
	ds_read_b128 v[118:121], v85 offset:4096
	s_waitcnt lgkmcnt(0)
	v_mfma_f32_32x32x16_bf16 v[48:63], v[106:109], v[110:113], v[48:63]
	v_mfma_f32_32x32x16_bf16 v[16:31], v[106:109], v[114:117], v[16:31]
	v_mfma_f32_32x32x16_bf16 v[32:47], v[118:121], v[110:113], v[32:47]
	v_mfma_f32_32x32x16_bf16 v[0:15], v[118:121], v[114:117], v[0:15]
	ds_read_b128 v[106:109], v88
	ds_read_b128 v[110:113], v89
	ds_read_b128 v[114:117], v89 offset:4096
	ds_read_b128 v[118:121], v88 offset:4096
	s_waitcnt vmcnt(6)
	s_barrier
; #define MFMA32(a, b, c) __builtin_amdgcn_mfma_f32_32x32x16_bf16((a), (b), (c), 0, 0, 0)
; template <int NI>
; DEVINL void gemm_kloop(const bf16_t* __restrict__ A, int lda, const bf16_t* __restrict__ Bt, int ldb, int K, int m0, int n0,
;                        unsigned char* lds, f32x16 (&acc)[NI][2]) {
;     ...
;     auto compute = [&](int st_) {
;         const unsigned char* pa = lds + st_ * STAGE + (wm * 64 + r) * 128;
;         const unsigned char* pb = lds + st_ * STAGE + A_ST + (wn * 32 * NI + r) * 128;
;         bf16x8 af[2][2], bfr[2][NI];
; #pragma unroll
;         for (int i = 0; i < 2; ++i) af[0][i] = *(const bf16x8*)(pa + i * 32 * 128 + o4[0]);
; #pragma unroll
;         for (int i = 0; i < NI; ++i) bfr[0][i] = *(const bf16x8*)(pb + i * 32 * 128 + o4[0]);
; #pragma unroll
;         for (int ks = 0; ks < 4; ++ks) {
;             if (ks < 3) {
; #pragma unroll
;                 for (int i = 0; i < 2; ++i) af[(ks + 1) & 1][i] = *(const bf16x8*)(pa + i * 32 * 128 + o4[ks + 1]);
; #pragma unroll
;                 for (int i = 0; i < NI; ++i) bfr[(ks + 1) & 1][i] = *(const bf16x8*)(pb + i * 32 * 128 + o4[ks + 1]);
;             }
; #pragma unroll
;             for (int ni = 0; ni < NI; ++ni)
; #pragma unroll
;                 for (int mi = 0; mi < 2; ++mi) acc[ni][mi] = MFMA32(bfr[ks & 1][ni], af[ks & 1][mi], acc[ni][mi]);
;         }
;     };
;     int t = 0;
;     for (; t + 2 < nt; ++t) {
;         if (NI == 2) asm volatile("s_waitcnt vmcnt(6)" ::: "memory"); else asm volatile("s_waitcnt vmcnt(5)" ::: "memory");
;         __builtin_amdgcn_s_barrier();
;         { const int s2 = (cur >= 1) ? cur - 1 : 2; GEMM_ISSUE(s2, t + 2); }
;         compute(cur);
;         cur = (cur == 2) ? 0 : cur + 1;
;     }
	s_waitcnt lgkmcnt(0)
	v_mfma_f32_32x32x16_bf16 v[48:63], v[106:109], v[110:113], v[48:63]
	v_mfma_f32_32x32x16_bf16 v[16:31], v[106:109], v[114:117], v[16:31]
	v_lshl_add_u64 v[106:107], v[66:67], 0, s[26:27]
	global_load_lds_dwordx4 v[106:107], off
	v_lshl_add_u64 v[106:107], v[66:67], 0, s[28:29]
	s_mov_b32 m0, s18
	s_nop 0
	global_load_lds_dwordx4 v[106:107], off
	v_lshl_add_u64 v[106:107], v[66:67], 0, s[30:31]
	s_mov_b32 m0, s19
	s_mov_b64 s[18:19], 0x60400
	global_load_lds_dwordx4 v[106:107], off
	v_lshl_add_u64 v[106:107], v[66:67], 0, s[18:19]
	s_mov_b32 m0, s20
	v_mfma_f32_32x32x16_bf16 v[32:47], v[118:121], v[110:113], v[32:47]
	global_load_lds_dwordx4 v[106:107], off
	v_lshl_add_u64 v[106:107], v[68:69], 0, s[26:27]
	s_mov_b32 m0, s21
	s_mov_b64 s[18:19], 0x480
	global_load_lds_dwordx4 v[106:107], off
	v_lshl_add_u64 v[106:107], v[68:69], 0, s[28:29]
	s_mov_b32 m0, s24
	v_mfma_f32_32x32x16_bf16 v[0:15], v[118:121], v[114:117], v[0:15]
	global_load_lds_dwordx4 v[106:107], off
	ds_read_b128 v[106:109], v64 offset:32768
	ds_read_b128 v[110:113], v71
	ds_read_b128 v[114:117], v71 offset:4096
	ds_read_b128 v[118:121], v64 offset:36864
	s_mov_b32 m0, s11
	s_mov_b64 s[20:21], 0x20480
	s_mov_b64 s[24:25], 0x40480
	v_readfirstlane_b32 s11, v103
	s_waitcnt lgkmcnt(0)
	v_mfma_f32_32x32x16_bf16 v[48:63], v[106:109], v[110:113], v[48:63]
	s_mov_b64 s[26:27], 0x600
	s_mov_b64 s[28:29], 0x20600
	s_mov_b64 s[30:31], 0x20680
	v_mfma_f32_32x32x16_bf16 v[16:31], v[106:109], v[114:117], v[16:31]
	v_mfma_f32_32x32x16_bf16 v[32:47], v[118:121], v[110:113], v[32:47]
	v_mfma_f32_32x32x16_bf16 v[0:15], v[118:121], v[114:117], v[0:15]
	ds_read_b128 v[106:109], v70 offset:32768
	ds_read_b128 v[110:113], v74
	ds_read_b128 v[114:117], v74 offset:4096
	ds_read_b128 v[118:121], v70 offset:36864
	s_waitcnt lgkmcnt(0)
	v_mfma_f32_32x32x16_bf16 v[48:63], v[106:109], v[110:113], v[48:63]
	v_mfma_f32_32x32x16_bf16 v[16:31], v[106:109], v[114:117], v[16:31]
	v_mfma_f32_32x32x16_bf16 v[32:47], v[118:121], v[110:113], v[32:47]
	v_mfma_f32_32x32x16_bf16 v[0:15], v[118:121], v[114:117], v[0:15]
	ds_read_b128 v[106:109], v72 offset:32768
	ds_read_b128 v[110:113], v76
	ds_read_b128 v[114:117], v76 offset:4096
	ds_read_b128 v[118:121], v72 offset:36864
	s_waitcnt lgkmcnt(0)
	v_mfma_f32_32x32x16_bf16 v[48:63], v[106:109], v[110:113], v[48:63]
	v_mfma_f32_32x32x16_bf16 v[16:31], v[106:109], v[114:117], v[16:31]
	v_mfma_f32_32x32x16_bf16 v[32:47], v[118:121], v[110:113], v[32:47]
	v_mfma_f32_32x32x16_bf16 v[0:15], v[118:121], v[114:117], v[0:15]
	ds_read_b128 v[106:109], v75 offset:32768
	ds_read_b128 v[110:113], v77
	ds_read_b128 v[114:117], v77 offset:4096
	ds_read_b128 v[118:121], v75 offset:36864
	s_waitcnt vmcnt(6)
	s_barrier
	s_waitcnt lgkmcnt(0)
	v_mfma_f32_32x32x16_bf16 v[48:63], v[106:109], v[110:113], v[48:63]
	v_mfma_f32_32x32x16_bf16 v[16:31], v[106:109], v[114:117], v[16:31]
	v_lshl_add_u64 v[106:107], v[66:67], 0, s[18:19]
	global_load_lds_dwordx4 v[106:107], off
	v_lshl_add_u64 v[106:107], v[66:67], 0, s[20:21]
	s_mov_b32 m0, s12
	s_nop 0
	global_load_lds_dwordx4 v[106:107], off
	v_lshl_add_u64 v[106:107], v[66:67], 0, s[24:25]
	s_mov_b32 m0, s13
	s_mov_b64 s[12:13], 0x60480
	global_load_lds_dwordx4 v[106:107], off
	v_lshl_add_u64 v[106:107], v[66:67], 0, s[12:13]
	s_mov_b32 m0, s14
	v_mfma_f32_32x32x16_bf16 v[32:47], v[118:121], v[110:113], v[32:47]
	global_load_lds_dwordx4 v[106:107], off
	v_lshl_add_u64 v[106:107], v[68:69], 0, s[18:19]
	s_mov_b32 m0, s15
	s_mov_b64 s[14:15], 0x500
	global_load_lds_dwordx4 v[106:107], off
	v_lshl_add_u64 v[106:107], v[68:69], 0, s[20:21]
	s_mov_b32 m0, s16
	v_mfma_f32_32x32x16_bf16 v[0:15], v[118:121], v[114:117], v[0:15]
	global_load_lds_dwordx4 v[106:107], off
	ds_read_b128 v[106:109], v78
	ds_read_b128 v[110:113], v71 offset:49152
	ds_read_b128 v[114:117], v71 offset:53248
	ds_read_b128 v[118:121], v78 offset:4096
	s_mov_b32 m0, s11
	s_mov_b64 s[16:17], 0x20500
	v_readfirstlane_b32 s12, v104
	s_mov_b64 s[18:19], 0x40500
	s_waitcnt lgkmcnt(0)
	v_mfma_f32_32x32x16_bf16 v[48:63], v[106:109], v[110:113], v[48:63]
	v_lshl_add_u64 v[104:105], v[66:67], 0, s[18:19]
	s_mov_b64 s[18:19], 0x60500
	v_readfirstlane_b32 s13, v97
	s_mov_b64 s[20:21], 0x20580
	s_mov_b64 s[24:25], 0x40600
	v_mfma_f32_32x32x16_bf16 v[16:31], v[106:109], v[114:117], v[16:31]
	v_mfma_f32_32x32x16_bf16 v[32:47], v[118:121], v[110:113], v[32:47]
	v_mfma_f32_32x32x16_bf16 v[0:15], v[118:121], v[114:117], v[0:15]
	ds_read_b128 v[106:109], v79
	ds_read_b128 v[110:113], v74 offset:49152
	ds_read_b128 v[114:117], v74 offset:53248
	ds_read_b128 v[118:121], v79 offset:4096
	s_waitcnt lgkmcnt(0)
	v_mfma_f32_32x32x16_bf16 v[48:63], v[106:109], v[110:113], v[48:63]
	v_mfma_f32_32x32x16_bf16 v[16:31], v[106:109], v[114:117], v[16:31]
	v_mfma_f32_32x32x16_bf16 v[32:47], v[118:121], v[110:113], v[32:47]
	v_mfma_f32_32x32x16_bf16 v[0:15], v[118:121], v[114:117], v[0:15]
	ds_read_b128 v[106:109], v80
	ds_read_b128 v[110:113], v76 offset:49152
	ds_read_b128 v[114:117], v76 offset:53248
	ds_read_b128 v[118:121], v80 offset:4096
	s_waitcnt lgkmcnt(0)
	v_mfma_f32_32x32x16_bf16 v[48:63], v[106:109], v[110:113], v[48:63]
	v_mfma_f32_32x32x16_bf16 v[16:31], v[106:109], v[114:117], v[16:31]
	v_mfma_f32_32x32x16_bf16 v[32:47], v[118:121], v[110:113], v[32:47]
	v_mfma_f32_32x32x16_bf16 v[0:15], v[118:121], v[114:117], v[0:15]
	ds_read_b128 v[106:109], v81
	ds_read_b128 v[110:113], v77 offset:49152
	ds_read_b128 v[114:117], v77 offset:53248
	ds_read_b128 v[118:121], v81 offset:4096
	s_waitcnt vmcnt(6)
	s_barrier
; #define MFMA32(a, b, c) __builtin_amdgcn_mfma_f32_32x32x16_bf16((a), (b), (c), 0, 0, 0)
; template <int NI>
; DEVINL void gemm_kloop(const bf16_t* __restrict__ A, int lda, const bf16_t* __restrict__ Bt, int ldb, int K, int m0, int n0,
;                        unsigned char* lds, f32x16 (&acc)[NI][2]) {
;     ...
;     auto compute = [&](int st_) {
;         const unsigned char* pa = lds + st_ * STAGE + (wm * 64 + r) * 128;
;         const unsigned char* pb = lds + st_ * STAGE + A_ST + (wn * 32 * NI + r) * 128;
;         bf16x8 af[2][2], bfr[2][NI];
; #pragma unroll
;         for (int i = 0; i < 2; ++i) af[0][i] = *(const bf16x8*)(pa + i * 32 * 128 + o4[0]);
; #pragma unroll
;         for (int i = 0; i < NI; ++i) bfr[0][i] = *(const bf16x8*)(pb + i * 32 * 128 + o4[0]);
; #pragma unroll
;         for (int ks = 0; ks < 4; ++ks) {
;             if (ks < 3) {
; #pragma unroll
;                 for (int i = 0; i < 2; ++i) af[(ks + 1) & 1][i] = *(const bf16x8*)(pa + i * 32 * 128 + o4[ks + 1]);
; #pragma unroll
;                 for (int i = 0; i < NI; ++i) bfr[(ks + 1) & 1][i] = *(const bf16x8*)(pb + i * 32 * 128 + o4[ks + 1]);
;             }
; #pragma unroll
;             for (int ni = 0; ni < NI; ++ni)
; #pragma unroll
;                 for (int mi = 0; mi < 2; ++mi) acc[ni][mi] = MFMA32(bfr[ks & 1][ni], af[ks & 1][mi], acc[ni][mi]);
;         }
;     };
;     int t = 0;
;     for (; t + 2 < nt; ++t) {
;         if (NI == 2) asm volatile("s_waitcnt vmcnt(6)" ::: "memory"); else asm volatile("s_waitcnt vmcnt(5)" ::: "memory");
;         __builtin_amdgcn_s_barrier();
;         { const int s2 = (cur >= 1) ? cur - 1 : 2; GEMM_ISSUE(s2, t + 2); }
;         compute(cur);
;         cur = (cur == 2) ? 0 : cur + 1;
;     }
	s_waitcnt lgkmcnt(0)
	v_mfma_f32_32x32x16_bf16 v[48:63], v[106:109], v[110:113], v[48:63]
	v_mfma_f32_32x32x16_bf16 v[16:31], v[106:109], v[114:117], v[16:31]
	v_lshl_add_u64 v[106:107], v[66:67], 0, s[14:15]
	global_load_lds_dwordx4 v[106:107], off
	v_lshl_add_u64 v[106:107], v[66:67], 0, s[16:17]
	s_mov_b32 m0, s12
	s_nop 0
	global_load_lds_dwordx4 v[106:107], off
	s_mov_b32 m0, s7
	v_mfma_f32_32x32x16_bf16 v[32:47], v[118:121], v[110:113], v[32:47]
	global_load_lds_dwordx4 v[104:105], off
	v_lshl_add_u64 v[104:105], v[66:67], 0, s[18:19]
	s_mov_b32 m0, s8
	s_mov_b64 s[18:19], 0x580
	global_load_lds_dwordx4 v[104:105], off
	v_lshl_add_u64 v[104:105], v[68:69], 0, s[14:15]
	s_mov_b32 m0, s9
	v_mfma_f32_32x32x16_bf16 v[0:15], v[118:121], v[114:117], v[0:15]
	global_load_lds_dwordx4 v[104:105], off
	v_lshl_add_u64 v[104:105], v[68:69], 0, s[16:17]
	s_mov_b32 m0, s10
	v_readfirstlane_b32 s14, v98
	global_load_lds_dwordx4 v[104:105], off
	ds_read_b128 v[104:107], v82
	ds_read_b128 v[108:111], v84
	ds_read_b128 v[112:115], v84 offset:4096
	ds_read_b128 v[116:119], v82 offset:4096
	s_waitcnt lgkmcnt(0)
	v_mfma_f32_32x32x16_bf16 v[48:63], v[104:107], v[108:111], v[48:63]
	s_mov_b32 m0, s13
	s_mov_b64 s[16:17], 0x40580
	v_readfirstlane_b32 s15, v99
	v_mfma_f32_32x32x16_bf16 v[16:31], v[104:107], v[112:115], v[16:31]
	v_mfma_f32_32x32x16_bf16 v[32:47], v[116:119], v[108:111], v[32:47]
	v_mfma_f32_32x32x16_bf16 v[0:15], v[116:119], v[112:115], v[0:15]
	ds_read_b128 v[104:107], v83
	ds_read_b128 v[108:111], v86
	ds_read_b128 v[112:115], v86 offset:4096
	ds_read_b128 v[116:119], v83 offset:4096
	s_waitcnt lgkmcnt(0)
	v_mfma_f32_32x32x16_bf16 v[48:63], v[104:107], v[108:111], v[48:63]
	v_mfma_f32_32x32x16_bf16 v[16:31], v[104:107], v[112:115], v[16:31]
	v_mfma_f32_32x32x16_bf16 v[32:47], v[116:119], v[108:111], v[32:47]
	v_mfma_f32_32x32x16_bf16 v[0:15], v[116:119], v[112:115], v[0:15]
	ds_read_b128 v[104:107], v85
	ds_read_b128 v[108:111], v87
	ds_read_b128 v[112:115], v87 offset:4096
	ds_read_b128 v[116:119], v85 offset:4096
	s_waitcnt lgkmcnt(0)
	v_mfma_f32_32x32x16_bf16 v[48:63], v[104:107], v[108:111], v[48:63]
	v_mfma_f32_32x32x16_bf16 v[16:31], v[104:107], v[112:115], v[16:31]
	v_mfma_f32_32x32x16_bf16 v[32:47], v[116:119], v[108:111], v[32:47]
	v_mfma_f32_32x32x16_bf16 v[0:15], v[116:119], v[112:115], v[0:15]
	ds_read_b128 v[104:107], v88
	ds_read_b128 v[108:111], v89
	ds_read_b128 v[112:115], v89 offset:4096
	ds_read_b128 v[116:119], v88 offset:4096
	s_waitcnt vmcnt(6)
	s_barrier
	s_waitcnt lgkmcnt(0)
	v_mfma_f32_32x32x16_bf16 v[48:63], v[104:107], v[108:111], v[48:63]
	v_mfma_f32_32x32x16_bf16 v[16:31], v[104:107], v[112:115], v[16:31]
	v_lshl_add_u64 v[104:105], v[66:67], 0, s[18:19]
	global_load_lds_dwordx4 v[104:105], off
	v_lshl_add_u64 v[104:105], v[66:67], 0, s[20:21]
	s_mov_b32 m0, s14
	s_nop 0
	global_load_lds_dwordx4 v[104:105], off
	v_lshl_add_u64 v[104:105], v[66:67], 0, s[16:17]
	s_mov_b64 s[16:17], 0x60580
	s_mov_b32 m0, s15
	v_lshl_add_u64 v[98:99], v[66:67], 0, s[16:17]
	v_readfirstlane_b32 s16, v100
	global_load_lds_dwordx4 v[104:105], off
	s_mov_b32 m0, s16
	v_readfirstlane_b32 s17, v101
	global_load_lds_dwordx4 v[98:99], off
	v_lshl_add_u64 v[98:99], v[68:69], 0, s[18:19]
	s_mov_b32 m0, s17
	v_readfirstlane_b32 s18, v102
	global_load_lds_dwordx4 v[98:99], off
	v_lshl_add_u64 v[98:99], v[68:69], 0, s[20:21]
	s_mov_b32 m0, s18
	v_mfma_f32_32x32x16_bf16 v[32:47], v[116:119], v[108:111], v[32:47]
	global_load_lds_dwordx4 v[98:99], off
	v_readfirstlane_b32 s19, v91
	s_mov_b32 m0, s19
	v_readfirstlane_b32 s20, v93
	v_readfirstlane_b32 s21, v94
	v_mov_b32_e32 v93, 0
	v_mfma_f32_32x32x16_bf16 v[0:15], v[116:119], v[112:115], v[0:15]
	ds_read_b128 v[98:101], v64 offset:32768
	ds_read_b128 v[102:105], v71
	ds_read_b128 v[106:109], v71 offset:4096
	ds_read_b128 v[110:113], v64 offset:36864
	s_waitcnt lgkmcnt(0)
	v_mfma_f32_32x32x16_bf16 v[48:63], v[98:101], v[102:105], v[48:63]
	v_mfma_f32_32x32x16_bf16 v[16:31], v[98:101], v[106:109], v[16:31]
	v_mfma_f32_32x32x16_bf16 v[32:47], v[110:113], v[102:105], v[32:47]
	v_mfma_f32_32x32x16_bf16 v[0:15], v[110:113], v[106:109], v[0:15]
	ds_read_b128 v[98:101], v70 offset:32768
	ds_read_b128 v[102:105], v74
	ds_read_b128 v[106:109], v74 offset:4096
	ds_read_b128 v[110:113], v70 offset:36864
	s_waitcnt lgkmcnt(0)
	v_mfma_f32_32x32x16_bf16 v[48:63], v[98:101], v[102:105], v[48:63]
	v_mfma_f32_32x32x16_bf16 v[16:31], v[98:101], v[106:109], v[16:31]
	v_mfma_f32_32x32x16_bf16 v[32:47], v[110:113], v[102:105], v[32:47]
	v_mfma_f32_32x32x16_bf16 v[0:15], v[110:113], v[106:109], v[0:15]
	ds_read_b128 v[98:101], v72 offset:32768
	ds_read_b128 v[102:105], v76
	ds_read_b128 v[106:109], v76 offset:4096
	ds_read_b128 v[110:113], v72 offset:36864
	s_waitcnt lgkmcnt(0)
	v_mfma_f32_32x32x16_bf16 v[48:63], v[98:101], v[102:105], v[48:63]
	v_mfma_f32_32x32x16_bf16 v[16:31], v[98:101], v[106:109], v[16:31]
	v_mfma_f32_32x32x16_bf16 v[32:47], v[110:113], v[102:105], v[32:47]
	v_mfma_f32_32x32x16_bf16 v[0:15], v[110:113], v[106:109], v[0:15]
	ds_read_b128 v[98:101], v75 offset:32768
	ds_read_b128 v[102:105], v77
	ds_read_b128 v[106:109], v77 offset:4096
	ds_read_b128 v[110:113], v75 offset:36864
	s_waitcnt vmcnt(6)
	s_barrier
; #define MFMA32(a, b, c) __builtin_amdgcn_mfma_f32_32x32x16_bf16((a), (b), (c), 0, 0, 0)
; template <int NI>
; DEVINL void gemm_kloop(const bf16_t* __restrict__ A, int lda, const bf16_t* __restrict__ Bt, int ldb, int K, int m0, int n0,
;                        unsigned char* lds, f32x16 (&acc)[NI][2]) {
;     ...
;     auto compute = [&](int st_) {
;         const unsigned char* pa = lds + st_ * STAGE + (wm * 64 + r) * 128;
;         const unsigned char* pb = lds + st_ * STAGE + A_ST + (wn * 32 * NI + r) * 128;
;         bf16x8 af[2][2], bfr[2][NI];
; #pragma unroll
;         for (int i = 0; i < 2; ++i) af[0][i] = *(const bf16x8*)(pa + i * 32 * 128 + o4[0]);
; #pragma unroll
;         for (int i = 0; i < NI; ++i) bfr[0][i] = *(const bf16x8*)(pb + i * 32 * 128 + o4[0]);
; #pragma unroll
;         for (int ks = 0; ks < 4; ++ks) {
;             if (ks < 3) {
; #pragma unroll
;                 for (int i = 0; i < 2; ++i) af[(ks + 1) & 1][i] = *(const bf16x8*)(pa + i * 32 * 128 + o4[ks + 1]);
; #pragma unroll
;                 for (int i = 0; i < NI; ++i) bfr[(ks + 1) & 1][i] = *(const bf16x8*)(pb + i * 32 * 128 + o4[ks + 1]);
;             }
; #pragma unroll
;             for (int ni = 0; ni < NI; ++ni)
; #pragma unroll
;                 for (int mi = 0; mi < 2; ++mi) acc[ni][mi] = MFMA32(bfr[ks & 1][ni], af[ks & 1][mi], acc[ni][mi]);
;         }
;     };
;     int t = 0;
;     for (; t + 2 < nt; ++t) {
;         if (NI == 2) asm volatile("s_waitcnt vmcnt(6)" ::: "memory"); else asm volatile("s_waitcnt vmcnt(5)" ::: "memory");
;         __builtin_amdgcn_s_barrier();
;         { const int s2 = (cur >= 1) ? cur - 1 : 2; GEMM_ISSUE(s2, t + 2); }
;         compute(cur);
;         cur = (cur == 2) ? 0 : cur + 1;
;     }
	s_waitcnt lgkmcnt(0)
	v_mfma_f32_32x32x16_bf16 v[48:63], v[98:101], v[102:105], v[48:63]
	v_mfma_f32_32x32x16_bf16 v[16:31], v[98:101], v[106:109], v[16:31]
	v_lshl_add_u64 v[98:99], v[66:67], 0, s[26:27]
	global_load_lds_dwordx4 v[98:99], off
	v_lshl_add_u64 v[98:99], v[66:67], 0, s[28:29]
	s_mov_b32 m0, s20
	s_nop 0
	global_load_lds_dwordx4 v[98:99], off
	v_lshl_add_u64 v[98:99], v[66:67], 0, s[24:25]
	s_mov_b32 m0, s21
	s_mov_b64 s[24:25], 0x60600
	global_load_lds_dwordx4 v[98:99], off
	v_lshl_add_u64 v[98:99], v[66:67], 0, s[24:25]
	v_readfirstlane_b32 s24, v96
	s_mov_b32 m0, s24
	v_readfirstlane_b32 s25, v90
	v_mfma_f32_32x32x16_bf16 v[32:47], v[110:113], v[102:105], v[32:47]
	global_load_lds_dwordx4 v[98:99], off
	v_lshl_add_u64 v[96:97], v[68:69], 0, s[26:27]
	s_mov_b32 m0, s25
	v_readfirstlane_b32 s26, v95
	global_load_lds_dwordx4 v[96:97], off
	v_mfma_f32_32x32x16_bf16 v[0:15], v[110:113], v[106:109], v[0:15]
	v_lshl_add_u64 v[90:91], v[68:69], 0, s[28:29]
	s_mov_b32 m0, s26
	s_mov_b64 s[28:29], 0x680
	global_load_lds_dwordx4 v[90:91], off
	ds_read_b128 v[94:97], v78
	ds_read_b128 v[98:101], v71 offset:49152
	ds_read_b128 v[102:105], v71 offset:53248
	ds_read_b128 v[106:109], v78 offset:4096
	v_lshl_add_u64 v[90:91], v[66:67], 0, s[28:29]
	s_waitcnt lgkmcnt(0)
	v_mfma_f32_32x32x16_bf16 v[48:63], v[94:97], v[98:101], v[48:63]
	s_mov_b32 m0, s11
	v_mfma_f32_32x32x16_bf16 v[16:31], v[94:97], v[102:105], v[16:31]
	v_mfma_f32_32x32x16_bf16 v[32:47], v[106:109], v[98:101], v[32:47]
	v_mfma_f32_32x32x16_bf16 v[0:15], v[106:109], v[102:105], v[0:15]
	ds_read_b128 v[94:97], v79
	ds_read_b128 v[98:101], v74 offset:49152
	ds_read_b128 v[102:105], v74 offset:53248
	ds_read_b128 v[106:109], v79 offset:4096
	s_waitcnt lgkmcnt(0)
	v_mfma_f32_32x32x16_bf16 v[48:63], v[94:97], v[98:101], v[48:63]
	v_mfma_f32_32x32x16_bf16 v[16:31], v[94:97], v[102:105], v[16:31]
	v_mfma_f32_32x32x16_bf16 v[32:47], v[106:109], v[98:101], v[32:47]
	v_mfma_f32_32x32x16_bf16 v[0:15], v[106:109], v[102:105], v[0:15]
	ds_read_b128 v[94:97], v80
	ds_read_b128 v[98:101], v76 offset:49152
	ds_read_b128 v[102:105], v76 offset:53248
	ds_read_b128 v[106:109], v80 offset:4096
	s_waitcnt lgkmcnt(0)
	v_mfma_f32_32x32x16_bf16 v[48:63], v[94:97], v[98:101], v[48:63]
	v_mfma_f32_32x32x16_bf16 v[16:31], v[94:97], v[102:105], v[16:31]
	v_mfma_f32_32x32x16_bf16 v[32:47], v[106:109], v[98:101], v[32:47]
	v_mfma_f32_32x32x16_bf16 v[0:15], v[106:109], v[102:105], v[0:15]
	ds_read_b128 v[94:97], v81
	ds_read_b128 v[98:101], v77 offset:49152
	ds_read_b128 v[102:105], v77 offset:53248
	ds_read_b128 v[106:109], v81 offset:4096
	s_waitcnt vmcnt(6)
	s_barrier
	global_load_lds_dwordx4 v[90:91], off
	v_lshl_add_u64 v[90:91], v[66:67], 0, s[30:31]
	s_mov_b32 m0, s12
	s_waitcnt lgkmcnt(0)
	v_mfma_f32_32x32x16_bf16 v[48:63], v[94:97], v[98:101], v[48:63]
	global_load_lds_dwordx4 v[90:91], off
	v_lshl_add_u64 v[90:91], v[66:67], 0, s[52:53]
	s_mov_b32 m0, s7
	s_mov_b64 s[52:53], 0x60680
	global_load_lds_dwordx4 v[90:91], off
	v_lshl_add_u64 v[90:91], v[66:67], 0, s[52:53]
	s_mov_b32 m0, s8
	v_mfma_f32_32x32x16_bf16 v[16:31], v[94:97], v[102:105], v[16:31]
	global_load_lds_dwordx4 v[90:91], off
	v_lshl_add_u64 v[90:91], v[68:69], 0, s[28:29]
	s_mov_b32 m0, s9
	s_mov_b64 s[8:9], 0x700
	global_load_lds_dwordx4 v[90:91], off
	v_mfma_f32_32x32x16_bf16 v[32:47], v[106:109], v[98:101], v[32:47]
	v_lshl_add_u64 v[90:91], v[68:69], 0, s[30:31]
	s_mov_b32 m0, s10
	s_mov_b64 s[10:11], 0x20700
	global_load_lds_dwordx4 v[90:91], off
	v_lshl_add_u64 v[90:91], v[66:67], 0, s[8:9]
	s_mov_b32 m0, s13
	v_mfma_f32_32x32x16_bf16 v[0:15], v[106:109], v[102:105], v[0:15]
	ds_read_b128 v[94:97], v82
	ds_read_b128 v[98:101], v84
	ds_read_b128 v[102:105], v84 offset:4096
	ds_read_b128 v[106:109], v82 offset:4096
	s_mov_b64 s[12:13], 0x40700
	s_waitcnt lgkmcnt(0)
	v_mfma_f32_32x32x16_bf16 v[48:63], v[94:97], v[98:101], v[48:63]
	v_mfma_f32_32x32x16_bf16 v[16:31], v[94:97], v[102:105], v[16:31]
	v_mfma_f32_32x32x16_bf16 v[32:47], v[106:109], v[98:101], v[32:47]
	v_mfma_f32_32x32x16_bf16 v[0:15], v[106:109], v[102:105], v[0:15]
	ds_read_b128 v[94:97], v83
	ds_read_b128 v[98:101], v86
	ds_read_b128 v[102:105], v86 offset:4096
	ds_read_b128 v[106:109], v83 offset:4096
	s_waitcnt lgkmcnt(0)
	v_mfma_f32_32x32x16_bf16 v[48:63], v[94:97], v[98:101], v[48:63]
	v_mfma_f32_32x32x16_bf16 v[16:31], v[94:97], v[102:105], v[16:31]
	v_mfma_f32_32x32x16_bf16 v[32:47], v[106:109], v[98:101], v[32:47]
	v_mfma_f32_32x32x16_bf16 v[0:15], v[106:109], v[102:105], v[0:15]
	ds_read_b128 v[94:97], v85
	ds_read_b128 v[98:101], v87
	ds_read_b128 v[102:105], v87 offset:4096
	ds_read_b128 v[106:109], v85 offset:4096
	s_waitcnt lgkmcnt(0)
	v_mfma_f32_32x32x16_bf16 v[48:63], v[94:97], v[98:101], v[48:63]
	v_mfma_f32_32x32x16_bf16 v[16:31], v[94:97], v[102:105], v[16:31]
	v_mfma_f32_32x32x16_bf16 v[32:47], v[106:109], v[98:101], v[32:47]
	v_mfma_f32_32x32x16_bf16 v[0:15], v[106:109], v[102:105], v[0:15]
	ds_read_b128 v[94:97], v88
	ds_read_b128 v[98:101], v89
	ds_read_b128 v[102:105], v89 offset:4096
	ds_read_b128 v[106:109], v88 offset:4096
	s_waitcnt vmcnt(6)
	s_barrier
; #define MFMA32(a, b, c) __builtin_amdgcn_mfma_f32_32x32x16_bf16((a), (b), (c), 0, 0, 0)
; template <int NI>
; DEVINL void gemm_kloop(const bf16_t* __restrict__ A, int lda, const bf16_t* __restrict__ Bt, int ldb, int K, int m0, int n0,
;                        unsigned char* lds, f32x16 (&acc)[NI][2]) {
;     ...
;     auto compute = [&](int st_) {
;         const unsigned char* pa = lds + st_ * STAGE + (wm * 64 + r) * 128;
;         const unsigned char* pb = lds + st_ * STAGE + A_ST + (wn * 32 * NI + r) * 128;
;         bf16x8 af[2][2], bfr[2][NI];
; #pragma unroll
;         for (int i = 0; i < 2; ++i) af[0][i] = *(const bf16x8*)(pa + i * 32 * 128 + o4[0]);
; #pragma unroll
;         for (int i = 0; i < NI; ++i) bfr[0][i] = *(const bf16x8*)(pb + i * 32 * 128 + o4[0]);
; #pragma unroll
;         for (int ks = 0; ks < 4; ++ks) {
;             if (ks < 3) {
; #pragma unroll
;                 for (int i = 0; i < 2; ++i) af[(ks + 1) & 1][i] = *(const bf16x8*)(pa + i * 32 * 128 + o4[ks + 1]);
; #pragma unroll
;                 for (int i = 0; i < NI; ++i) bfr[(ks + 1) & 1][i] = *(const bf16x8*)(pb + i * 32 * 128 + o4[ks + 1]);
;             }
; #pragma unroll
;             for (int ni = 0; ni < NI; ++ni)
; #pragma unroll
;                 for (int mi = 0; mi < 2; ++mi) acc[ni][mi] = MFMA32(bfr[ks & 1][ni], af[ks & 1][mi], acc[ni][mi]);
;         }
;     };
;     int t = 0;
;     for (; t + 2 < nt; ++t) {
;         if (NI == 2) asm volatile("s_waitcnt vmcnt(6)" ::: "memory"); else asm volatile("s_waitcnt vmcnt(5)" ::: "memory");
;         __builtin_amdgcn_s_barrier();
;         { const int s2 = (cur >= 1) ? cur - 1 : 2; GEMM_ISSUE(s2, t + 2); }
;         compute(cur);
;         cur = (cur == 2) ? 0 : cur + 1;
;     }
	global_load_lds_dwordx4 v[90:91], off
	v_lshl_add_u64 v[90:91], v[66:67], 0, s[10:11]
	s_mov_b32 m0, s14
	s_waitcnt lgkmcnt(0)
	v_mfma_f32_32x32x16_bf16 v[48:63], v[94:97], v[98:101], v[48:63]
	global_load_lds_dwordx4 v[90:91], off
	v_lshl_add_u64 v[90:91], v[66:67], 0, s[12:13]
	s_mov_b32 m0, s15
	s_mov_b64 s[12:13], 0x60700
	global_load_lds_dwordx4 v[90:91], off
	v_lshl_add_u64 v[90:91], v[66:67], 0, s[12:13]
	s_mov_b32 m0, s16
	v_mfma_f32_32x32x16_bf16 v[16:31], v[94:97], v[102:105], v[16:31]
	global_load_lds_dwordx4 v[90:91], off
	v_lshl_add_u64 v[90:91], v[68:69], 0, s[8:9]
	s_mov_b32 m0, s17
	s_mov_b64 s[8:9], 0x780
	global_load_lds_dwordx4 v[90:91], off
	v_mfma_f32_32x32x16_bf16 v[32:47], v[106:109], v[98:101], v[32:47]
	v_lshl_add_u64 v[90:91], v[68:69], 0, s[10:11]
	s_mov_b32 m0, s18
	s_mov_b64 s[10:11], 0x20780
	global_load_lds_dwordx4 v[90:91], off
	v_lshl_add_u64 v[90:91], v[66:67], 0, s[8:9]
	s_mov_b32 m0, s19
	v_mfma_f32_32x32x16_bf16 v[0:15], v[106:109], v[102:105], v[0:15]
	ds_read_b128 v[94:97], v64 offset:32768
	ds_read_b128 v[98:101], v71
	ds_read_b128 v[102:105], v71 offset:4096
	ds_read_b128 v[106:109], v64 offset:36864
	s_mov_b64 s[12:13], 0x40780
	s_waitcnt lgkmcnt(0)
	v_mfma_f32_32x32x16_bf16 v[48:63], v[94:97], v[98:101], v[48:63]
	v_mfma_f32_32x32x16_bf16 v[16:31], v[94:97], v[102:105], v[16:31]
	v_mfma_f32_32x32x16_bf16 v[32:47], v[106:109], v[98:101], v[32:47]
	v_mfma_f32_32x32x16_bf16 v[0:15], v[106:109], v[102:105], v[0:15]
	ds_read_b128 v[94:97], v70 offset:32768
	ds_read_b128 v[98:101], v74
	ds_read_b128 v[102:105], v74 offset:4096
	ds_read_b128 v[106:109], v70 offset:36864
	s_waitcnt lgkmcnt(0)
	v_mfma_f32_32x32x16_bf16 v[48:63], v[94:97], v[98:101], v[48:63]
	v_mfma_f32_32x32x16_bf16 v[16:31], v[94:97], v[102:105], v[16:31]
	v_mfma_f32_32x32x16_bf16 v[32:47], v[106:109], v[98:101], v[32:47]
	v_mfma_f32_32x32x16_bf16 v[0:15], v[106:109], v[102:105], v[0:15]
	ds_read_b128 v[94:97], v72 offset:32768
	ds_read_b128 v[98:101], v76
	ds_read_b128 v[102:105], v76 offset:4096
	ds_read_b128 v[106:109], v72 offset:36864
	s_waitcnt lgkmcnt(0)
	v_mfma_f32_32x32x16_bf16 v[48:63], v[94:97], v[98:101], v[48:63]
	v_mfma_f32_32x32x16_bf16 v[16:31], v[94:97], v[102:105], v[16:31]
	v_mfma_f32_32x32x16_bf16 v[32:47], v[106:109], v[98:101], v[32:47]
	v_mfma_f32_32x32x16_bf16 v[0:15], v[106:109], v[102:105], v[0:15]
	ds_read_b128 v[94:97], v75 offset:32768
	ds_read_b128 v[98:101], v77
	ds_read_b128 v[102:105], v77 offset:4096
	ds_read_b128 v[106:109], v75 offset:36864
	s_waitcnt vmcnt(6)
	s_barrier
	global_load_lds_dwordx4 v[90:91], off
	v_lshl_add_u64 v[90:91], v[66:67], 0, s[10:11]
	s_mov_b32 m0, s20
	s_waitcnt lgkmcnt(0)
	v_mfma_f32_32x32x16_bf16 v[48:63], v[94:97], v[98:101], v[48:63]
	global_load_lds_dwordx4 v[90:91], off
	v_lshl_add_u64 v[90:91], v[66:67], 0, s[12:13]
	s_mov_b32 m0, s21
	s_mov_b64 s[12:13], 0x60780
	global_load_lds_dwordx4 v[90:91], off
	v_lshl_add_u64 v[66:67], v[66:67], 0, s[12:13]
	s_mov_b32 m0, s24
	v_mfma_f32_32x32x16_bf16 v[16:31], v[94:97], v[102:105], v[16:31]
	global_load_lds_dwordx4 v[66:67], off
	v_lshl_add_u64 v[66:67], v[68:69], 0, s[8:9]
	s_mov_b32 m0, s25
	s_mov_b64 s[8:9], 0
	global_load_lds_dwordx4 v[66:67], off
	v_mfma_f32_32x32x16_bf16 v[32:47], v[106:109], v[98:101], v[32:47]
	v_lshl_add_u64 v[66:67], v[68:69], 0, s[10:11]
	s_mov_b32 m0, s26
	s_mov_b64 s[12:13], 0
	global_load_lds_dwordx4 v[66:67], off
	v_mfma_f32_32x32x16_bf16 v[0:15], v[106:109], v[102:105], v[0:15]
	ds_read_b128 v[66:69], v78
	ds_read_b128 v[94:97], v71 offset:49152
	ds_read_b128 v[98:101], v71 offset:53248
	ds_read_b128 v[102:105], v78 offset:4096
	s_waitcnt lgkmcnt(0)
	v_mfma_f32_32x32x16_bf16 v[48:63], v[66:69], v[94:97], v[48:63]
	v_mfma_f32_32x32x16_bf16 v[16:31], v[66:69], v[98:101], v[16:31]
	v_mfma_f32_32x32x16_bf16 v[32:47], v[102:105], v[94:97], v[32:47]
	v_mfma_f32_32x32x16_bf16 v[0:15], v[102:105], v[98:101], v[0:15]
	ds_read_b128 v[66:69], v79
	ds_read_b128 v[94:97], v74 offset:49152
	ds_read_b128 v[98:101], v74 offset:53248
	ds_read_b128 v[102:105], v79 offset:4096
	s_waitcnt lgkmcnt(0)
	v_mfma_f32_32x32x16_bf16 v[48:63], v[66:69], v[94:97], v[48:63]
	v_mfma_f32_32x32x16_bf16 v[16:31], v[66:69], v[98:101], v[16:31]
	v_mfma_f32_32x32x16_bf16 v[32:47], v[102:105], v[94:97], v[32:47]
	v_mfma_f32_32x32x16_bf16 v[0:15], v[102:105], v[98:101], v[0:15]
	ds_read_b128 v[66:69], v80
	ds_read_b128 v[94:97], v76 offset:49152
	ds_read_b128 v[98:101], v76 offset:53248
	ds_read_b128 v[102:105], v80 offset:4096
	s_waitcnt lgkmcnt(0)
	v_mfma_f32_32x32x16_bf16 v[48:63], v[66:69], v[94:97], v[48:63]
	v_mfma_f32_32x32x16_bf16 v[16:31], v[66:69], v[98:101], v[16:31]
	v_mfma_f32_32x32x16_bf16 v[32:47], v[102:105], v[94:97], v[32:47]
	v_mfma_f32_32x32x16_bf16 v[0:15], v[102:105], v[98:101], v[0:15]
	ds_read_b128 v[66:69], v81
	ds_read_b128 v[94:97], v77 offset:49152
	ds_read_b128 v[98:101], v77 offset:53248
	ds_read_b128 v[78:81], v81 offset:4096
	s_waitcnt vmcnt(6)
	s_barrier
; template <int NI>
; DEVINL void gemm_kloop(const bf16_t* __restrict__ A, int lda, const bf16_t* __restrict__ Bt, int ldb, int K, int m0, int n0,
;                        unsigned char* lds, f32x16 (&acc)[NI][2]) {
;     ...
;     if (nt >= 2) {
;         if (NI == 2) asm volatile("s_waitcnt vmcnt(6)" ::: "memory"); else asm volatile("s_waitcnt vmcnt(5)" ::: "memory");
;         __builtin_amdgcn_s_barrier();
;         compute(cur);
;         cur = (cur == 2) ? 0 : cur + 1;
;     }
;     asm volatile("s_waitcnt vmcnt(0)" ::: "memory");
;     __builtin_amdgcn_s_barrier();
;     compute(cur);
	s_waitcnt lgkmcnt(0)
	v_mfma_f32_32x32x16_bf16 v[48:63], v[66:69], v[94:97], v[48:63]
	v_mfma_f32_32x32x16_bf16 v[16:31], v[66:69], v[98:101], v[16:31]
	v_mfma_f32_32x32x16_bf16 v[32:47], v[78:81], v[94:97], v[32:47]
	v_mfma_f32_32x32x16_bf16 v[0:15], v[78:81], v[98:101], v[0:15]
	ds_read_b128 v[66:69], v82
	ds_read_b128 v[78:81], v84
	ds_read_b128 v[94:97], v84 offset:4096
	ds_read_b128 v[98:101], v82 offset:4096
	s_waitcnt lgkmcnt(0)
	v_mfma_f32_32x32x16_bf16 v[48:63], v[66:69], v[78:81], v[48:63]
	v_mfma_f32_32x32x16_bf16 v[16:31], v[66:69], v[94:97], v[16:31]
	v_mfma_f32_32x32x16_bf16 v[32:47], v[98:101], v[78:81], v[32:47]
	v_mfma_f32_32x32x16_bf16 v[0:15], v[98:101], v[94:97], v[0:15]
	ds_read_b128 v[66:69], v83
	ds_read_b128 v[78:81], v86
	ds_read_b128 v[94:97], v86 offset:4096
	ds_read_b128 v[98:101], v83 offset:4096
	s_waitcnt lgkmcnt(0)
	v_mfma_f32_32x32x16_bf16 v[48:63], v[66:69], v[78:81], v[48:63]
	v_mfma_f32_32x32x16_bf16 v[16:31], v[66:69], v[94:97], v[16:31]
	v_mfma_f32_32x32x16_bf16 v[32:47], v[98:101], v[78:81], v[32:47]
	v_mfma_f32_32x32x16_bf16 v[0:15], v[98:101], v[94:97], v[0:15]
	ds_read_b128 v[66:69], v85
	ds_read_b128 v[78:81], v87
	ds_read_b128 v[94:97], v87 offset:4096
	ds_read_b128 v[82:85], v85 offset:4096
	s_waitcnt lgkmcnt(0)
	v_mfma_f32_32x32x16_bf16 v[48:63], v[66:69], v[78:81], v[48:63]
	v_mfma_f32_32x32x16_bf16 v[16:31], v[66:69], v[94:97], v[16:31]
	v_mfma_f32_32x32x16_bf16 v[32:47], v[82:85], v[78:81], v[32:47]
	v_mfma_f32_32x32x16_bf16 v[0:15], v[82:85], v[94:97], v[0:15]
	ds_read_b128 v[66:69], v88
	ds_read_b128 v[78:81], v89
	ds_read_b128 v[82:85], v89 offset:4096
	ds_read_b128 v[86:89], v88 offset:4096
	s_waitcnt vmcnt(0)
	s_barrier
	v_mov_b32_e32 v94, 0
	s_waitcnt lgkmcnt(0)
	v_mfma_f32_32x32x16_bf16 v[48:63], v[66:69], v[78:81], v[48:63]
	v_mfma_f32_32x32x16_bf16 v[16:31], v[66:69], v[82:85], v[16:31]
	v_mfma_f32_32x32x16_bf16 v[32:47], v[86:89], v[78:81], v[32:47]
	v_mfma_f32_32x32x16_bf16 v[0:15], v[86:89], v[82:85], v[0:15]
	ds_read_b128 v[66:69], v64 offset:32768
	ds_read_b128 v[78:81], v71
	ds_read_b128 v[82:85], v71 offset:4096
	ds_read_b128 v[86:89], v64 offset:36864
	v_mov_b32_e32 v64, v160
	s_waitcnt lgkmcnt(0)
	v_mfma_f32_32x32x16_bf16 v[48:63], v[66:69], v[78:81], v[48:63]
	v_mfma_f32_32x32x16_bf16 v[16:31], v[66:69], v[82:85], v[16:31]
	v_mfma_f32_32x32x16_bf16 v[32:47], v[86:89], v[78:81], v[32:47]
	v_mfma_f32_32x32x16_bf16 v[0:15], v[86:89], v[82:85], v[0:15]
	ds_read_b128 v[66:69], v70 offset:32768
	ds_read_b128 v[78:81], v74
	ds_read_b128 v[82:85], v74 offset:4096
	ds_read_b128 v[86:89], v70 offset:36864
	v_mov_b64_e32 v[70:71], 0
	s_waitcnt lgkmcnt(0)
	v_mfma_f32_32x32x16_bf16 v[48:63], v[66:69], v[78:81], v[48:63]
	v_mfma_f32_32x32x16_bf16 v[16:31], v[66:69], v[82:85], v[16:31]
	v_mfma_f32_32x32x16_bf16 v[32:47], v[86:89], v[78:81], v[32:47]
	v_mfma_f32_32x32x16_bf16 v[0:15], v[86:89], v[82:85], v[0:15]
	ds_read_b128 v[66:69], v72 offset:32768
	ds_read_b128 v[78:81], v76
	ds_read_b128 v[82:85], v76 offset:4096
	ds_read_b128 v[86:89], v72 offset:36864
	v_mov_b32_e32 v72, 0x3e38aa3b
	s_waitcnt lgkmcnt(0)
	v_mfma_f32_32x32x16_bf16 v[48:63], v[66:69], v[78:81], v[48:63]
	v_mfma_f32_32x32x16_bf16 v[16:31], v[66:69], v[82:85], v[16:31]
	v_mfma_f32_32x32x16_bf16 v[32:47], v[86:89], v[78:81], v[32:47]
	v_mfma_f32_32x32x16_bf16 v[0:15], v[86:89], v[82:85], v[0:15]
	ds_read_b128 v[66:69], v75 offset:32768
	ds_read_b128 v[78:81], v77
	ds_read_b128 v[82:85], v77 offset:4096
	ds_read_b128 v[74:77], v75 offset:36864
	s_waitcnt lgkmcnt(0)
	v_readfirstlane_b32 s100, v200
	s_cmp_eq_u32 s100, 1
	s_cbranch_scc0 .Lip_nopf
	s_barrier
	v_lshlrev_b32_e32 v206, 4, v160
	v_mov_b32_e32 v212, 0x20000
	v_mov_b32_e32 v213, 0
	v_mov_b64_e32 v[210:211], v[202:203]
	v_readfirstlane_b32 s100, v206
	v_add_u32_e32 v206, 0x2000, v206
	s_mov_b32 m0, s100
	s_nop 0
	global_load_lds_dwordx4 v[210:211], off
	v_lshl_add_u64 v[210:211], v[210:211], 0, v[212:213]
	v_readfirstlane_b32 s100, v206
	v_add_u32_e32 v206, 0x2000, v206
	s_mov_b32 m0, s100
	s_nop 0
	global_load_lds_dwordx4 v[210:211], off
	v_lshl_add_u64 v[210:211], v[210:211], 0, v[212:213]
	v_readfirstlane_b32 s100, v206
	v_add_u32_e32 v206, 0x2000, v206
	s_mov_b32 m0, s100
	s_nop 0
	global_load_lds_dwordx4 v[210:211], off
	v_lshl_add_u64 v[210:211], v[210:211], 0, v[212:213]
	v_readfirstlane_b32 s100, v206
	v_add_u32_e32 v206, 0x2000, v206
	s_mov_b32 m0, s100
	s_nop 0
	global_load_lds_dwordx4 v[210:211], off
	v_lshl_add_u64 v[210:211], v[210:211], 0, v[212:213]
	v_mov_b64_e32 v[210:211], v[204:205]
	v_readfirstlane_b32 s100, v206
	v_add_u32_e32 v206, 0x2000, v206
	s_mov_b32 m0, s100
	s_nop 0
	global_load_lds_dwordx4 v[210:211], off
	v_lshl_add_u64 v[210:211], v[210:211], 0, v[212:213]
	v_readfirstlane_b32 s100, v206
	v_add_u32_e32 v206, 0x2000, v206
	s_mov_b32 m0, s100
	s_nop 0
	global_load_lds_dwordx4 v[210:211], off
	v_lshl_add_u64 v[210:211], v[210:211], 0, v[212:213]
	v_mov_b32_e32 v201, 1
	s_branch .Lip_pfdone
;     DEVINL bf16_t* AVT() const { return (bf16_t*)(ws + OFF_AVT); }
;     DEVINL bf16_t* BVT() const { return (bf16_t*)(ws + OFF_BVT); }
;     DEVINL bf16_t* DVT() const { return (bf16_t*)(ws + OFF_DVT); }
;     DEVINL bf16_t* BKT() const { return (bf16_t*)(ws + OFF_BKT); }
; #define TID (opq_v((int)threadIdx.x))
; DEVINL void epi_inproj(const Ctx& c, int layer, f32x16 (&acc)[2][2], int mbase, int nbase, unsigned char* lds) {
;     const int lane = TID & 63, r = lane & 31, h = lane >> 5;
;     const int n = nbase;
;     int zc = -1, tr = 0, vcol = 0, vC = 0; bf16_t* vt = nullptr; float scale = 1.f; const float* gain = nullptr;
;     if (n < 512) { zc = Z_AQ + n; scale = QS; }
;     else if (n < 1024) { zc = Z_AK + (n - 512); }
;     else if (n < 1536) { vt = c.AVT(); vcol = n - 1024; vC = 512; }
;     else if (n < 1792) { zc = Z_BQ + (n - 1536); }
;     else if (n < 2048) { zc = Z_BK + (n - 1792); scale = 0.125f; vt = c.BKT(); vcol = n - 1792; vC = 256; }
;     else if (n < 2560) { vt = c.BVT(); vcol = n - 2048; vC = 512; }
;     else if (n < 3072) { zc = Z_BG + (n - 2560); }
;     else if (n < 4864) { zc = Z_C + (n - 3072); }
;     else if (n < 5376) { zc = Z_DQ + (n - 4864); tr = 1; scale = QS; gain = c.in[I_QNG] + layer * 64; }
;     else if (n < 5504) { zc = Z_DK + (n - 5376); tr = 1; gain = c.in[I_KNG] + layer * 64; }
;     else if (n < 5632) { vt = c.DVT(); vcol = n - 5504; vC = 128; }
;     else if (n < 9728) { zc = Z_GZ + (n - 5632); tr = 2; }
;     else { zc = Z_VL + (n - 9728); }
.Lip_nopf:
	v_mov_b32_e32 v201, 0
.Lip_pfdone:
	v_mfma_f32_32x32x16_bf16 v[48:63], v[66:69], v[78:81], v[48:63]
	v_mfma_f32_32x32x16_bf16 v[16:31], v[66:69], v[82:85], v[16:31]
	v_add_u32_e32 v66, s6, v92
	s_movk_i32 s6, 0x1ff
	v_mov_b64_e32 v[68:69], 0
	v_cmp_lt_i32_e32 vcc, s6, v66
	v_mfma_f32_32x32x16_bf16 v[32:47], v[74:77], v[78:81], v[32:47]
	v_mfma_f32_32x32x16_bf16 v[0:15], v[74:77], v[82:85], v[0:15]
	s_and_saveexec_b64 s[6:7], vcc
	s_cbranch_execz .LBB0_404
	s_movk_i32 s8, 0x3ff
	v_cmp_lt_u32_e32 vcc, s8, v66
	v_mov_b32_e32 v72, 1.0
	v_mov_b64_e32 v[68:69], 0
	v_mov_b32_e32 v93, 0
	s_mov_b64 s[10:11], 0
	v_mov_b32_e32 v94, 0
	v_mov_b64_e32 v[70:71], 0
	s_and_saveexec_b64 s[8:9], vcc
	s_cbranch_execz .LBB0_403
	v_cmp_lt_u32_e32 vcc, s47, v66
	s_and_saveexec_b64 s[12:13], vcc
	s_xor_b64 s[12:13], exec, s[12:13]
	s_cbranch_execz .LBB0_400
	s_movk_i32 s10, 0x6ff
	v_cmp_lt_u32_e32 vcc, s10, v66
	s_and_saveexec_b64 s[16:17], vcc
	s_xor_b64 s[16:17], exec, s[16:17]
	s_cbranch_execz .LBB0_397
	s_movk_i32 s10, 0x7ff
	v_cmp_lt_u32_e32 vcc, s10, v66
	s_and_saveexec_b64 s[18:19], vcc
	s_xor_b64 s[18:19], exec, s[18:19]
	s_cbranch_execz .LBB0_394
	s_movk_i32 s10, 0x9ff
	v_cmp_lt_u32_e32 vcc, s10, v66
	s_and_saveexec_b64 s[20:21], vcc
	s_xor_b64 s[20:21], exec, s[20:21]
	s_cbranch_execz .LBB0_391
	s_movk_i32 s10, 0xbff
	v_cmp_lt_u32_e32 vcc, s10, v66
	s_and_saveexec_b64 s[24:25], vcc
	s_xor_b64 s[24:25], exec, s[24:25]
	s_cbranch_execz .LBB0_388
	s_movk_i32 s10, 0x12ff
	v_cmp_lt_u32_e32 vcc, s10, v66
	s_and_saveexec_b64 s[26:27], vcc
	s_xor_b64 s[26:27], exec, s[26:27]
	s_cbranch_execz .LBB0_385
	s_movk_i32 s10, 0x14ff
	v_cmp_lt_u32_e32 vcc, s10, v66
	s_and_saveexec_b64 s[28:29], vcc
	s_xor_b64 s[28:29], exec, s[28:29]
	s_cbranch_execz .LBB0_382
	s_movk_i32 s10, 0x157f
	v_cmp_lt_u32_e32 vcc, s10, v66
	s_and_saveexec_b64 s[14:15], vcc
	s_xor_b64 s[14:15], exec, s[14:15]
	s_cbranch_execz .LBB0_379
	s_movk_i32 s10, 0x15ff
	v_cmp_lt_u32_e32 vcc, s10, v66
	s_and_saveexec_b64 s[30:31], vcc
	s_xor_b64 s[30:31], exec, s[30:31]
	s_movk_i32 s10, 0x2600
	v_cmp_gt_u32_e64 s[10:11], s10, v66
	v_add_u32_e32 v66, 0xfffffb80, v66
	s_or_saveexec_b64 s[30:31], s[30:31]
	v_mov_b64_e32 v[68:69], 0
	v_mov_b32_e32 v93, 0
	v_mov_b32_e32 v94, 0
	s_xor_b64 exec, exec, s[30:31]
	s_cbranch_execz .LBB0_378
	v_readlane_b32 s38, v247, 45
	v_readlane_b32 s39, v247, 46
	v_add_u32_e32 v93, 0xffffea80, v66
	v_mov_b32_e32 v94, 0x80
	v_mov_b32_e32 v66, -1
	v_mov_b64_e32 v[68:69], s[38:39]
	s_andn2_b64 s[10:11], s[10:11], exec
